# ret_scan cross epilogue: two adjacent columns packed per lane via DPP so each register pair is written by one global_store_dword instead of two global_store_short
# speedup vs baseline: 1.0001x; 1.0001x over previous
.LBB0_327:
	v_mov_b32_e32 v130, s67
	v_mov_b32_e32 v131, s66
	v_cndmask_b32_e32 v130, v130, v131, vcc
	v_lshl_add_u32 v168, v130, 7, v155
	v_mov_b32_e32 v153, v161
	v_mov_b32_e32 v192, v181
	v_mov_b32_e32 v190, v183
	v_mov_b32_e32 v191, v182
	v_mov_b32_e32 v166, v157
	v_mov_b32_e32 v130, v186
	v_mov_b32_e32 v131, v187
	v_ashrrev_i32_e32 v169, 31, v168
	v_readfirstlane_b32 s64, v130
	v_readfirstlane_b32 s65, v131
	v_lshlrev_b64 v[130:131], 11, v[168:169]
	v_mov_b32_e32 v167, v189
	s_barrier
	v_lshl_add_u64 v[130:131], s[64:65], 0, v[130:131]
	v_lshl_add_u64 v[130:131], v[130:131], 0, v[0:1]
	v_bfe_u32 v132, v189, 6, 2
	v_lshlrev_b32_e32 v132, 5, v132
	v_bfe_u32 v133, v189, 5, 1
	v_add_u32_e32 v132, v132, v133
	v_lshlrev_b32_e32 v132, 11, v132
	v_and_b32_e32 v133, 31, v189
	v_lshl_add_u32 v132, v133, 4, v132
	v_mov_b32_e32 v133, 0
	v_lshl_add_u64 v[130:131], v[130:131], 0, v[132:133]
	s_mov_b32 s6, 0xc640000
	s_mov_b32 s7, 0
	v_lshl_add_u64 v[130:131], v[130:131], 0, s[6:7]
	v_readfirstlane_b32 s6, v149
	v_readfirstlane_b32 s7, v189
	s_nop 3
	s_bfe_u32 s7, s7, 0x20006
	s_mul_i32 s7, s7, 0x4100
	s_add_u32 s6, s6, s7
	s_mov_b32 m0, s6
	s_mov_b32 s6, 0x1000
	s_mov_b32 s7, 0
	global_load_lds_dwordx4 v[130:131], off
	s_add_u32 m0, m0, 0x410
	v_lshl_add_u64 v[130:131], v[130:131], 0, s[6:7]
	global_load_lds_dwordx4 v[130:131], off
	s_add_u32 m0, m0, 0x410
	v_lshl_add_u64 v[130:131], v[130:131], 0, s[6:7]
	global_load_lds_dwordx4 v[130:131], off
	s_add_u32 m0, m0, 0x410
	v_lshl_add_u64 v[130:131], v[130:131], 0, s[6:7]
	global_load_lds_dwordx4 v[130:131], off
	s_add_u32 m0, m0, 0x410
	v_lshl_add_u64 v[130:131], v[130:131], 0, s[6:7]
	global_load_lds_dwordx4 v[130:131], off
	s_add_u32 m0, m0, 0x410
	v_lshl_add_u64 v[130:131], v[130:131], 0, s[6:7]
	global_load_lds_dwordx4 v[130:131], off
	s_add_u32 m0, m0, 0x410
	v_lshl_add_u64 v[130:131], v[130:131], 0, s[6:7]
	global_load_lds_dwordx4 v[130:131], off
	s_add_u32 m0, m0, 0x410
	v_lshl_add_u64 v[130:131], v[130:131], 0, s[6:7]
	global_load_lds_dwordx4 v[130:131], off
	s_add_u32 m0, m0, 0x410
	v_lshl_add_u64 v[130:131], v[130:131], 0, s[6:7]
	global_load_lds_dwordx4 v[130:131], off
	s_add_u32 m0, m0, 0x410
	v_lshl_add_u64 v[130:131], v[130:131], 0, s[6:7]
	global_load_lds_dwordx4 v[130:131], off
	s_add_u32 m0, m0, 0x410
	v_lshl_add_u64 v[130:131], v[130:131], 0, s[6:7]
	global_load_lds_dwordx4 v[130:131], off
	s_add_u32 m0, m0, 0x410
	v_lshl_add_u64 v[130:131], v[130:131], 0, s[6:7]
	global_load_lds_dwordx4 v[130:131], off
	s_add_u32 m0, m0, 0x410
	v_lshl_add_u64 v[130:131], v[130:131], 0, s[6:7]
	global_load_lds_dwordx4 v[130:131], off
	s_add_u32 m0, m0, 0x410
	v_lshl_add_u64 v[130:131], v[130:131], 0, s[6:7]
	global_load_lds_dwordx4 v[130:131], off
	s_add_u32 m0, m0, 0x410
	v_lshl_add_u64 v[130:131], v[130:131], 0, s[6:7]
	global_load_lds_dwordx4 v[130:131], off
	s_add_u32 m0, m0, 0x410
	v_lshl_add_u64 v[130:131], v[130:131], 0, s[6:7]
	global_load_lds_dwordx4 v[130:131], off
	v_lshl_add_u64 v[210:211], s[64:65], 0, v[162:163]
	s_waitcnt vmcnt(0)
	s_waitcnt lgkmcnt(0)
	s_barrier
	v_ashrrev_i32_e32 v167, 31, v166
	v_lshl_add_u64 v[130:131], v[166:167], 1, v[210:211]
	s_mov_b64 s[6:7], 0x8640000
	v_lshl_add_u64 v[170:171], v[130:131], 0, s[6:7]
	v_add_u32_e32 v250, 0x4000, v178
	ds_read2_b64 v[194:197], v178 offset0:0 offset1:2
	ds_read2_b64 v[218:221], v250 offset0:32 offset1:34
	ds_read2_b64 v[222:225], v178 offset0:4 offset1:6
	ds_read2_b64 v[226:229], v250 offset0:36 offset1:38
	s_nop 0
	v_cvt_pk_bf16_f32 v230, v2, v3
	v_cvt_pk_bf16_f32 v231, v4, v5
	v_cvt_pk_bf16_f32 v232, v6, v7
	v_cvt_pk_bf16_f32 v233, v8, v9
	s_waitcnt lgkmcnt(2)
	s_nop 1
	v_mfma_f32_32x32x16_bf16 v[130:145], v[194:197], v[230:233], 0
	v_mfma_f32_32x32x16_bf16 v[234:249], v[218:221], v[230:233], 0
	ds_read2_b64 v[194:197], v178 offset0:8 offset1:10
	ds_read2_b64 v[218:221], v250 offset0:40 offset1:42
	s_nop 0
	v_cvt_pk_bf16_f32 v230, v10, v11
	v_cvt_pk_bf16_f32 v231, v12, v13
	v_cvt_pk_bf16_f32 v232, v14, v15
	v_cvt_pk_bf16_f32 v233, v16, v17
	s_waitcnt lgkmcnt(2)
	s_nop 1
	v_mfma_f32_32x32x16_bf16 v[130:145], v[222:225], v[230:233], v[130:145]
	v_mfma_f32_32x32x16_bf16 v[234:249], v[226:229], v[230:233], v[234:249]
	ds_read2_b64 v[222:225], v178 offset0:12 offset1:14
	ds_read2_b64 v[226:229], v250 offset0:44 offset1:46
	s_nop 0
	v_cvt_pk_bf16_f32 v230, v18, v19
	v_cvt_pk_bf16_f32 v231, v20, v21
	v_cvt_pk_bf16_f32 v232, v22, v23
	v_cvt_pk_bf16_f32 v233, v24, v25
	s_waitcnt lgkmcnt(2)
	s_nop 1
	v_mfma_f32_32x32x16_bf16 v[130:145], v[194:197], v[230:233], v[130:145]
	v_mfma_f32_32x32x16_bf16 v[234:249], v[218:221], v[230:233], v[234:249]
	ds_read2_b64 v[194:197], v178 offset0:16 offset1:18
	ds_read2_b64 v[218:221], v250 offset0:48 offset1:50
	s_nop 0
	v_cvt_pk_bf16_f32 v230, v26, v27
	v_cvt_pk_bf16_f32 v231, v28, v29
	v_cvt_pk_bf16_f32 v232, v30, v31
	v_cvt_pk_bf16_f32 v233, v32, v33
	s_waitcnt lgkmcnt(2)
	s_nop 1
	v_mfma_f32_32x32x16_bf16 v[130:145], v[222:225], v[230:233], v[130:145]
	v_mfma_f32_32x32x16_bf16 v[234:249], v[226:229], v[230:233], v[234:249]
	ds_read2_b64 v[222:225], v178 offset0:20 offset1:22
	ds_read2_b64 v[226:229], v250 offset0:52 offset1:54
	s_nop 0
	v_cvt_pk_bf16_f32 v230, v34, v35
	v_cvt_pk_bf16_f32 v231, v36, v37
	v_cvt_pk_bf16_f32 v232, v38, v39
	v_cvt_pk_bf16_f32 v233, v40, v41
	s_waitcnt lgkmcnt(2)
	s_nop 1
	v_mfma_f32_32x32x16_bf16 v[130:145], v[194:197], v[230:233], v[130:145]
	v_mfma_f32_32x32x16_bf16 v[234:249], v[218:221], v[230:233], v[234:249]
	ds_read2_b64 v[194:197], v178 offset0:24 offset1:26
	ds_read2_b64 v[218:221], v250 offset0:56 offset1:58
	s_nop 0
	v_cvt_pk_bf16_f32 v230, v42, v43
	v_cvt_pk_bf16_f32 v231, v44, v45
	v_cvt_pk_bf16_f32 v232, v46, v47
	v_cvt_pk_bf16_f32 v233, v48, v49
	s_waitcnt lgkmcnt(2)
	s_nop 1
	v_mfma_f32_32x32x16_bf16 v[130:145], v[222:225], v[230:233], v[130:145]
	v_mfma_f32_32x32x16_bf16 v[234:249], v[226:229], v[230:233], v[234:249]
	ds_read2_b64 v[222:225], v178 offset0:28 offset1:30
	ds_read2_b64 v[226:229], v250 offset0:60 offset1:62
	s_nop 0
	v_cvt_pk_bf16_f32 v230, v50, v51
	v_cvt_pk_bf16_f32 v231, v52, v53
	v_cvt_pk_bf16_f32 v232, v54, v55
	v_cvt_pk_bf16_f32 v233, v56, v57
	s_waitcnt lgkmcnt(2)
	s_nop 1
	v_mfma_f32_32x32x16_bf16 v[130:145], v[194:197], v[230:233], v[130:145]
	v_mfma_f32_32x32x16_bf16 v[234:249], v[218:221], v[230:233], v[234:249]
	ds_read2_b64 v[194:197], v178 offset0:32 offset1:34
	ds_read2_b64 v[218:221], v250 offset0:64 offset1:66
	s_nop 0
	v_cvt_pk_bf16_f32 v230, v58, v59
	v_cvt_pk_bf16_f32 v231, v60, v61
	v_cvt_pk_bf16_f32 v232, v62, v63
	v_cvt_pk_bf16_f32 v233, v64, v65
	s_waitcnt lgkmcnt(2)
	s_nop 1
	v_mfma_f32_32x32x16_bf16 v[130:145], v[222:225], v[230:233], v[130:145]
	v_mfma_f32_32x32x16_bf16 v[234:249], v[226:229], v[230:233], v[234:249]
	ds_read2_b64 v[222:225], v178 offset0:36 offset1:38
	ds_read2_b64 v[226:229], v250 offset0:68 offset1:70
	s_nop 0
	v_cvt_pk_bf16_f32 v230, v66, v67
	v_cvt_pk_bf16_f32 v231, v68, v69
	v_cvt_pk_bf16_f32 v232, v70, v71
	v_cvt_pk_bf16_f32 v233, v72, v73
	s_waitcnt lgkmcnt(2)
	s_nop 1
	v_mfma_f32_32x32x16_bf16 v[130:145], v[194:197], v[230:233], v[130:145]
	v_mfma_f32_32x32x16_bf16 v[234:249], v[218:221], v[230:233], v[234:249]
	ds_read2_b64 v[194:197], v178 offset0:40 offset1:42
	ds_read2_b64 v[218:221], v250 offset0:72 offset1:74
	s_nop 0
	v_cvt_pk_bf16_f32 v230, v74, v75
	v_cvt_pk_bf16_f32 v231, v76, v77
	v_cvt_pk_bf16_f32 v232, v78, v79
	v_cvt_pk_bf16_f32 v233, v80, v81
	s_waitcnt lgkmcnt(2)
	s_nop 1
	v_mfma_f32_32x32x16_bf16 v[130:145], v[222:225], v[230:233], v[130:145]
	v_mfma_f32_32x32x16_bf16 v[234:249], v[226:229], v[230:233], v[234:249]
	ds_read2_b64 v[222:225], v178 offset0:44 offset1:46
	ds_read2_b64 v[226:229], v250 offset0:76 offset1:78
	s_nop 0
	v_cvt_pk_bf16_f32 v230, v82, v83
	v_cvt_pk_bf16_f32 v231, v84, v85
	v_cvt_pk_bf16_f32 v232, v86, v87
	v_cvt_pk_bf16_f32 v233, v88, v89
	s_waitcnt lgkmcnt(2)
	s_nop 1
	v_mfma_f32_32x32x16_bf16 v[130:145], v[194:197], v[230:233], v[130:145]
	v_mfma_f32_32x32x16_bf16 v[234:249], v[218:221], v[230:233], v[234:249]
	ds_read2_b64 v[194:197], v178 offset0:48 offset1:50
	ds_read2_b64 v[218:221], v250 offset0:80 offset1:82
	s_nop 0
	v_cvt_pk_bf16_f32 v230, v90, v91
	v_cvt_pk_bf16_f32 v231, v92, v93
	v_cvt_pk_bf16_f32 v232, v94, v95
	v_cvt_pk_bf16_f32 v233, v96, v97
	s_waitcnt lgkmcnt(2)
	s_nop 1
	v_mfma_f32_32x32x16_bf16 v[130:145], v[222:225], v[230:233], v[130:145]
	v_mfma_f32_32x32x16_bf16 v[234:249], v[226:229], v[230:233], v[234:249]
	ds_read2_b64 v[222:225], v178 offset0:52 offset1:54
	ds_read2_b64 v[226:229], v250 offset0:84 offset1:86
	s_nop 0
	v_cvt_pk_bf16_f32 v230, v98, v99
	v_cvt_pk_bf16_f32 v231, v100, v101
	v_cvt_pk_bf16_f32 v232, v102, v103
	v_cvt_pk_bf16_f32 v233, v104, v105
	s_waitcnt lgkmcnt(2)
	s_nop 1
	v_mfma_f32_32x32x16_bf16 v[130:145], v[194:197], v[230:233], v[130:145]
	v_mfma_f32_32x32x16_bf16 v[234:249], v[218:221], v[230:233], v[234:249]
	ds_read2_b64 v[194:197], v178 offset0:56 offset1:58
	ds_read2_b64 v[218:221], v250 offset0:88 offset1:90
	s_nop 0
	v_cvt_pk_bf16_f32 v230, v106, v107
	v_cvt_pk_bf16_f32 v231, v108, v109
	v_cvt_pk_bf16_f32 v232, v110, v111
	v_cvt_pk_bf16_f32 v233, v112, v113
	s_waitcnt lgkmcnt(2)
	s_nop 1
	v_mfma_f32_32x32x16_bf16 v[130:145], v[222:225], v[230:233], v[130:145]
	v_mfma_f32_32x32x16_bf16 v[234:249], v[226:229], v[230:233], v[234:249]
	ds_read2_b64 v[222:225], v178 offset0:60 offset1:62
	ds_read2_b64 v[226:229], v250 offset0:92 offset1:94
	s_nop 0
	v_cvt_pk_bf16_f32 v230, v114, v115
	v_cvt_pk_bf16_f32 v231, v116, v117
	v_cvt_pk_bf16_f32 v232, v118, v119
	v_cvt_pk_bf16_f32 v233, v120, v121
	s_waitcnt lgkmcnt(2)
	s_nop 1
	v_mfma_f32_32x32x16_bf16 v[130:145], v[194:197], v[230:233], v[130:145]
	v_mfma_f32_32x32x16_bf16 v[234:249], v[218:221], v[230:233], v[234:249]
	s_nop 0
	v_cvt_pk_bf16_f32 v230, v122, v123
	v_cvt_pk_bf16_f32 v231, v124, v125
	v_cvt_pk_bf16_f32 v232, v126, v127
	v_cvt_pk_bf16_f32 v233, v128, v129
	s_waitcnt lgkmcnt(0)
	s_nop 1
	v_mfma_f32_32x32x16_bf16 v[130:145], v[222:225], v[230:233], v[130:145]
	v_mfma_f32_32x32x16_bf16 v[234:249], v[226:229], v[230:233], v[234:249]
	v_or_b32_e32 v172, v168, v174
	v_ashrrev_i32_e32 v173, 31, v172
	v_lshlrev_b64 v[172:173], 12, v[172:173]
	s_mov_b32 s100, 0xaaaaaaaa
	s_mov_b32 s101, 0xaaaaaaaa
	v_and_b32_e32 v220, 1, v189
	v_mul_u32_u24_e32 v220, 0xffe, v220
	v_mov_b32_e32 v221, 0
	v_lshl_add_u64 v[218:219], v[170:171], 0, v[172:173]
	v_lshl_add_u64 v[218:219], v[218:219], 0, v[220:221]
	s_mov_b32 s7, 0
	s_nop 7
	v_fma_f32 v222, 0, v192, v153
	v_add_f32_e32 v223, v153, v192
	v_exp_f32_e32 v222, v222
	v_exp_f32_e32 v223, v223
	s_nop 0
	v_mul_f32_e32 v222, v222, v130
	v_mul_f32_e32 v223, v223, v131
	s_nop 1
	v_mov_b32_dpp v224, v222 quad_perm:[1,0,3,2] row_mask:0xf bank_mask:0xf
	v_mov_b32_dpp v225, v223 quad_perm:[1,0,3,2] row_mask:0xf bank_mask:0xf
	v_cndmask_b32_e64 v226, v222, v225, s[100:101]
	v_cndmask_b32_e64 v227, v224, v223, s[100:101]
	v_cvt_pk_bf16_f32 v226, v226, v227
	s_mov_b32 s6, 0x0
	v_lshl_add_u64 v[228:229], v[218:219], 0, s[6:7]
	global_store_dword v[228:229], v226, off
	v_fma_f32 v222, 2.0, v192, v153
	v_fmamk_f32 v223, v192, 0x40400000, v153
	v_exp_f32_e32 v222, v222
	v_exp_f32_e32 v223, v223
	s_nop 0
	v_mul_f32_e32 v222, v222, v132
	v_mul_f32_e32 v223, v223, v133
	s_nop 1
	v_mov_b32_dpp v224, v222 quad_perm:[1,0,3,2] row_mask:0xf bank_mask:0xf
	v_mov_b32_dpp v225, v223 quad_perm:[1,0,3,2] row_mask:0xf bank_mask:0xf
	v_cndmask_b32_e64 v226, v222, v225, s[100:101]
	v_cndmask_b32_e64 v227, v224, v223, s[100:101]
	v_cvt_pk_bf16_f32 v226, v226, v227
	s_mov_b32 s6, 0x2000
	v_lshl_add_u64 v[228:229], v[218:219], 0, s[6:7]
	global_store_dword v[228:229], v226, off
	v_fmamk_f32 v222, v192, 0x41000000, v153
	v_fmamk_f32 v223, v192, 0x41100000, v153
	v_exp_f32_e32 v222, v222
	v_exp_f32_e32 v223, v223
	s_nop 0
	v_mul_f32_e32 v222, v222, v134
	v_mul_f32_e32 v223, v223, v135
	s_nop 1
	v_mov_b32_dpp v224, v222 quad_perm:[1,0,3,2] row_mask:0xf bank_mask:0xf
	v_mov_b32_dpp v225, v223 quad_perm:[1,0,3,2] row_mask:0xf bank_mask:0xf
	v_cndmask_b32_e64 v226, v222, v225, s[100:101]
	v_cndmask_b32_e64 v227, v224, v223, s[100:101]
	v_cvt_pk_bf16_f32 v226, v226, v227
	s_mov_b32 s6, 0x8000
	v_lshl_add_u64 v[228:229], v[218:219], 0, s[6:7]
	global_store_dword v[228:229], v226, off
	v_fmamk_f32 v222, v192, 0x41200000, v153
	v_fmamk_f32 v223, v192, 0x41300000, v153
	v_exp_f32_e32 v222, v222
	v_exp_f32_e32 v223, v223
	s_nop 0
	v_mul_f32_e32 v222, v222, v136
	v_mul_f32_e32 v223, v223, v137
	s_nop 1
	v_mov_b32_dpp v224, v222 quad_perm:[1,0,3,2] row_mask:0xf bank_mask:0xf
	v_mov_b32_dpp v225, v223 quad_perm:[1,0,3,2] row_mask:0xf bank_mask:0xf
	v_cndmask_b32_e64 v226, v222, v225, s[100:101]
	v_cndmask_b32_e64 v227, v224, v223, s[100:101]
	v_cvt_pk_bf16_f32 v226, v226, v227
	s_mov_b32 s6, 0xa000
	v_lshl_add_u64 v[228:229], v[218:219], 0, s[6:7]
	global_store_dword v[228:229], v226, off
	v_fmamk_f32 v222, v192, 0x41800000, v153
	v_fmamk_f32 v223, v192, 0x41880000, v153
	v_exp_f32_e32 v222, v222
	v_exp_f32_e32 v223, v223
	s_nop 0
	v_mul_f32_e32 v222, v222, v138
	v_mul_f32_e32 v223, v223, v139
	s_nop 1
	v_mov_b32_dpp v224, v222 quad_perm:[1,0,3,2] row_mask:0xf bank_mask:0xf
	v_mov_b32_dpp v225, v223 quad_perm:[1,0,3,2] row_mask:0xf bank_mask:0xf
	v_cndmask_b32_e64 v226, v222, v225, s[100:101]
	v_cndmask_b32_e64 v227, v224, v223, s[100:101]
	v_cvt_pk_bf16_f32 v226, v226, v227
	s_mov_b32 s6, 0x10000
	v_lshl_add_u64 v[228:229], v[218:219], 0, s[6:7]
	global_store_dword v[228:229], v226, off
	v_fmamk_f32 v222, v192, 0x41900000, v153
	v_fmamk_f32 v223, v192, 0x41980000, v153
	v_exp_f32_e32 v222, v222
	v_exp_f32_e32 v223, v223
	s_nop 0
	v_mul_f32_e32 v222, v222, v140
	v_mul_f32_e32 v223, v223, v141
	s_nop 1
	v_mov_b32_dpp v224, v222 quad_perm:[1,0,3,2] row_mask:0xf bank_mask:0xf
	v_mov_b32_dpp v225, v223 quad_perm:[1,0,3,2] row_mask:0xf bank_mask:0xf
	v_cndmask_b32_e64 v226, v222, v225, s[100:101]
	v_cndmask_b32_e64 v227, v224, v223, s[100:101]
	v_cvt_pk_bf16_f32 v226, v226, v227
	s_mov_b32 s6, 0x12000
	v_lshl_add_u64 v[228:229], v[218:219], 0, s[6:7]
	global_store_dword v[228:229], v226, off
	v_fmamk_f32 v222, v192, 0x41c00000, v153
	v_fmamk_f32 v223, v192, 0x41c80000, v153
	v_exp_f32_e32 v222, v222
	v_exp_f32_e32 v223, v223
	s_nop 0
	v_mul_f32_e32 v222, v222, v142
	v_mul_f32_e32 v223, v223, v143
	s_nop 1
	v_mov_b32_dpp v224, v222 quad_perm:[1,0,3,2] row_mask:0xf bank_mask:0xf
	v_mov_b32_dpp v225, v223 quad_perm:[1,0,3,2] row_mask:0xf bank_mask:0xf
	v_cndmask_b32_e64 v226, v222, v225, s[100:101]
	v_cndmask_b32_e64 v227, v224, v223, s[100:101]
	v_cvt_pk_bf16_f32 v226, v226, v227
	s_mov_b32 s6, 0x18000
	v_lshl_add_u64 v[228:229], v[218:219], 0, s[6:7]
	global_store_dword v[228:229], v226, off
	v_fmamk_f32 v222, v192, 0x41d00000, v153
	v_fmamk_f32 v223, v192, 0x41d80000, v153
	v_exp_f32_e32 v222, v222
	v_exp_f32_e32 v223, v223
	s_nop 0
	v_mul_f32_e32 v222, v222, v144
	v_mul_f32_e32 v223, v223, v145
	s_nop 1
	v_mov_b32_dpp v224, v222 quad_perm:[1,0,3,2] row_mask:0xf bank_mask:0xf
	v_mov_b32_dpp v225, v223 quad_perm:[1,0,3,2] row_mask:0xf bank_mask:0xf
	v_cndmask_b32_e64 v226, v222, v225, s[100:101]
	v_cndmask_b32_e64 v227, v224, v223, s[100:101]
	v_cvt_pk_bf16_f32 v226, v226, v227
	s_mov_b32 s6, 0x1a000
	v_lshl_add_u64 v[228:229], v[218:219], 0, s[6:7]
	global_store_dword v[228:229], v226, off
	v_mov_b32_e32 v130, v234
	v_mov_b32_e32 v131, v235
	v_mov_b32_e32 v132, v236
	v_mov_b32_e32 v133, v237
	v_mov_b32_e32 v134, v238
	v_mov_b32_e32 v135, v239
	v_mov_b32_e32 v136, v240
	v_mov_b32_e32 v137, v241
	v_mov_b32_e32 v138, v242
	v_mov_b32_e32 v139, v243
	v_mov_b32_e32 v140, v244
	v_mov_b32_e32 v141, v245
	v_mov_b32_e32 v142, v246
	v_mov_b32_e32 v143, v247
	v_mov_b32_e32 v144, v248
	v_mov_b32_e32 v145, v249
	s_mov_b32 s100, 0xaaaaaaaa
	s_mov_b32 s101, 0xaaaaaaaa
	v_and_b32_e32 v220, 1, v189
	v_mul_u32_u24_e32 v220, 0xffe, v220
	v_mov_b32_e32 v221, 0
	v_lshl_add_u64 v[218:219], v[170:171], 0, v[172:173]
	v_lshl_add_u64 v[218:219], v[218:219], 0, v[220:221]
	s_mov_b32 s7, 0
	s_nop 7
	v_fmamk_f32 v222, v192, 0x42000000, v153
	v_fmamk_f32 v223, v192, 0x42040000, v153
	v_exp_f32_e32 v222, v222
	v_exp_f32_e32 v223, v223
	s_nop 0
	v_mul_f32_e32 v222, v222, v130
	v_mul_f32_e32 v223, v223, v131
	s_nop 1
	v_mov_b32_dpp v224, v222 quad_perm:[1,0,3,2] row_mask:0xf bank_mask:0xf
	v_mov_b32_dpp v225, v223 quad_perm:[1,0,3,2] row_mask:0xf bank_mask:0xf
	v_cndmask_b32_e64 v226, v222, v225, s[100:101]
	v_cndmask_b32_e64 v227, v224, v223, s[100:101]
	v_cvt_pk_bf16_f32 v226, v226, v227
	s_mov_b32 s6, 0x20000
	v_lshl_add_u64 v[228:229], v[218:219], 0, s[6:7]
	global_store_dword v[228:229], v226, off
	v_fmamk_f32 v222, v192, 0x42080000, v153
	v_fmamk_f32 v223, v192, 0x420c0000, v153
	v_exp_f32_e32 v222, v222
	v_exp_f32_e32 v223, v223
	s_nop 0
	v_mul_f32_e32 v222, v222, v132
	v_mul_f32_e32 v223, v223, v133
	s_nop 1
	v_mov_b32_dpp v224, v222 quad_perm:[1,0,3,2] row_mask:0xf bank_mask:0xf
	v_mov_b32_dpp v225, v223 quad_perm:[1,0,3,2] row_mask:0xf bank_mask:0xf
	v_cndmask_b32_e64 v226, v222, v225, s[100:101]
	v_cndmask_b32_e64 v227, v224, v223, s[100:101]
	v_cvt_pk_bf16_f32 v226, v226, v227
	s_mov_b32 s6, 0x22000
	v_lshl_add_u64 v[228:229], v[218:219], 0, s[6:7]
	global_store_dword v[228:229], v226, off
	v_fmamk_f32 v222, v192, 0x42200000, v153
	v_fmamk_f32 v223, v192, 0x42240000, v153
	v_exp_f32_e32 v222, v222
	v_exp_f32_e32 v223, v223
	s_nop 0
	v_mul_f32_e32 v222, v222, v134
	v_mul_f32_e32 v223, v223, v135
	s_nop 1
	v_mov_b32_dpp v224, v222 quad_perm:[1,0,3,2] row_mask:0xf bank_mask:0xf
	v_mov_b32_dpp v225, v223 quad_perm:[1,0,3,2] row_mask:0xf bank_mask:0xf
	v_cndmask_b32_e64 v226, v222, v225, s[100:101]
	v_cndmask_b32_e64 v227, v224, v223, s[100:101]
	v_cvt_pk_bf16_f32 v226, v226, v227
	s_mov_b32 s6, 0x28000
	v_lshl_add_u64 v[228:229], v[218:219], 0, s[6:7]
	global_store_dword v[228:229], v226, off
	v_fmamk_f32 v222, v192, 0x42280000, v153
	v_fmamk_f32 v223, v192, 0x422c0000, v153
	v_exp_f32_e32 v222, v222
	v_exp_f32_e32 v223, v223
	s_nop 0
	v_mul_f32_e32 v222, v222, v136
	v_mul_f32_e32 v223, v223, v137
	s_nop 1
	v_mov_b32_dpp v224, v222 quad_perm:[1,0,3,2] row_mask:0xf bank_mask:0xf
	v_mov_b32_dpp v225, v223 quad_perm:[1,0,3,2] row_mask:0xf bank_mask:0xf
	v_cndmask_b32_e64 v226, v222, v225, s[100:101]
	v_cndmask_b32_e64 v227, v224, v223, s[100:101]
	v_cvt_pk_bf16_f32 v226, v226, v227
	s_mov_b32 s6, 0x2a000
	v_lshl_add_u64 v[228:229], v[218:219], 0, s[6:7]
	global_store_dword v[228:229], v226, off
	v_fmamk_f32 v222, v192, 0x42400000, v153
	v_fmamk_f32 v223, v192, 0x42440000, v153
	v_exp_f32_e32 v222, v222
	v_exp_f32_e32 v223, v223
	s_nop 0
	v_mul_f32_e32 v222, v222, v138
	v_mul_f32_e32 v223, v223, v139
	s_nop 1
	v_mov_b32_dpp v224, v222 quad_perm:[1,0,3,2] row_mask:0xf bank_mask:0xf
	v_mov_b32_dpp v225, v223 quad_perm:[1,0,3,2] row_mask:0xf bank_mask:0xf
	v_cndmask_b32_e64 v226, v222, v225, s[100:101]
	v_cndmask_b32_e64 v227, v224, v223, s[100:101]
	v_cvt_pk_bf16_f32 v226, v226, v227
	s_mov_b32 s6, 0x30000
	v_lshl_add_u64 v[228:229], v[218:219], 0, s[6:7]
	global_store_dword v[228:229], v226, off
	v_fmamk_f32 v222, v192, 0x42480000, v153
	v_fmamk_f32 v223, v192, 0x424c0000, v153
	v_exp_f32_e32 v222, v222
	v_exp_f32_e32 v223, v223
	s_nop 0
	v_mul_f32_e32 v222, v222, v140
	v_mul_f32_e32 v223, v223, v141
	s_nop 1
	v_mov_b32_dpp v224, v222 quad_perm:[1,0,3,2] row_mask:0xf bank_mask:0xf
	v_mov_b32_dpp v225, v223 quad_perm:[1,0,3,2] row_mask:0xf bank_mask:0xf
	v_cndmask_b32_e64 v226, v222, v225, s[100:101]
	v_cndmask_b32_e64 v227, v224, v223, s[100:101]
	v_cvt_pk_bf16_f32 v226, v226, v227
	s_mov_b32 s6, 0x32000
	v_lshl_add_u64 v[228:229], v[218:219], 0, s[6:7]
	global_store_dword v[228:229], v226, off
	v_fmamk_f32 v222, v192, 0x42600000, v153
	v_fmamk_f32 v223, v192, 0x42640000, v153
	v_exp_f32_e32 v222, v222
	v_exp_f32_e32 v223, v223
	s_nop 0
	v_mul_f32_e32 v222, v222, v142
	v_mul_f32_e32 v223, v223, v143
	s_nop 1
	v_mov_b32_dpp v224, v222 quad_perm:[1,0,3,2] row_mask:0xf bank_mask:0xf
	v_mov_b32_dpp v225, v223 quad_perm:[1,0,3,2] row_mask:0xf bank_mask:0xf
	v_cndmask_b32_e64 v226, v222, v225, s[100:101]
	v_cndmask_b32_e64 v227, v224, v223, s[100:101]
	v_cvt_pk_bf16_f32 v226, v226, v227
	s_mov_b32 s6, 0x38000
	v_lshl_add_u64 v[228:229], v[218:219], 0, s[6:7]
	global_store_dword v[228:229], v226, off
	v_fmamk_f32 v222, v192, 0x42680000, v153
	v_fmamk_f32 v223, v192, 0x426c0000, v153
	v_exp_f32_e32 v222, v222
	v_exp_f32_e32 v223, v223
	s_nop 0
	v_mul_f32_e32 v222, v222, v144
	v_mul_f32_e32 v223, v223, v145
	s_nop 1
	v_mov_b32_dpp v224, v222 quad_perm:[1,0,3,2] row_mask:0xf bank_mask:0xf
	v_mov_b32_dpp v225, v223 quad_perm:[1,0,3,2] row_mask:0xf bank_mask:0xf
	v_cndmask_b32_e64 v226, v222, v225, s[100:101]
	v_cndmask_b32_e64 v227, v224, v223, s[100:101]
	v_cvt_pk_bf16_f32 v226, v226, v227
	s_mov_b32 s6, 0x3a000
	v_lshl_add_u64 v[228:229], v[218:219], 0, s[6:7]
	global_store_dword v[228:229], v226, off
	v_add_u32_e32 v250, 0xc000, v178
	v_add_u32_e32 v251, 0x8000, v178
	ds_read2_b64 v[194:197], v251 offset0:64 offset1:66
	ds_read2_b64 v[218:221], v250 offset0:96 offset1:98
	ds_read2_b64 v[222:225], v251 offset0:68 offset1:70
	ds_read2_b64 v[226:229], v250 offset0:100 offset1:102
	s_nop 0
	v_cvt_pk_bf16_f32 v230, v2, v3
	v_cvt_pk_bf16_f32 v231, v4, v5
	v_cvt_pk_bf16_f32 v232, v6, v7
	v_cvt_pk_bf16_f32 v233, v8, v9
	s_waitcnt lgkmcnt(2)
	s_nop 1
	v_mfma_f32_32x32x16_bf16 v[130:145], v[194:197], v[230:233], 0
	v_mfma_f32_32x32x16_bf16 v[234:249], v[218:221], v[230:233], 0
	ds_read2_b64 v[194:197], v251 offset0:72 offset1:74
	ds_read2_b64 v[218:221], v250 offset0:104 offset1:106
	s_nop 0
	v_cvt_pk_bf16_f32 v230, v10, v11
	v_cvt_pk_bf16_f32 v231, v12, v13
	v_cvt_pk_bf16_f32 v232, v14, v15
	v_cvt_pk_bf16_f32 v233, v16, v17
	s_waitcnt lgkmcnt(2)
	s_nop 1
	v_mfma_f32_32x32x16_bf16 v[130:145], v[222:225], v[230:233], v[130:145]
	v_mfma_f32_32x32x16_bf16 v[234:249], v[226:229], v[230:233], v[234:249]
	ds_read2_b64 v[222:225], v251 offset0:76 offset1:78
	ds_read2_b64 v[226:229], v250 offset0:108 offset1:110
	s_nop 0
	v_cvt_pk_bf16_f32 v230, v18, v19
	v_cvt_pk_bf16_f32 v231, v20, v21
	v_cvt_pk_bf16_f32 v232, v22, v23
	v_cvt_pk_bf16_f32 v233, v24, v25
	s_waitcnt lgkmcnt(2)
	s_nop 1
	v_mfma_f32_32x32x16_bf16 v[130:145], v[194:197], v[230:233], v[130:145]
	v_mfma_f32_32x32x16_bf16 v[234:249], v[218:221], v[230:233], v[234:249]
	ds_read2_b64 v[194:197], v251 offset0:80 offset1:82
	ds_read2_b64 v[218:221], v250 offset0:112 offset1:114
	s_nop 0
	v_cvt_pk_bf16_f32 v230, v26, v27
	v_cvt_pk_bf16_f32 v231, v28, v29
	v_cvt_pk_bf16_f32 v232, v30, v31
	v_cvt_pk_bf16_f32 v233, v32, v33
	s_waitcnt lgkmcnt(2)
	s_nop 1
	v_mfma_f32_32x32x16_bf16 v[130:145], v[222:225], v[230:233], v[130:145]
	v_mfma_f32_32x32x16_bf16 v[234:249], v[226:229], v[230:233], v[234:249]
	ds_read2_b64 v[222:225], v251 offset0:84 offset1:86
	ds_read2_b64 v[226:229], v250 offset0:116 offset1:118
	s_nop 0
	v_cvt_pk_bf16_f32 v230, v34, v35
	v_cvt_pk_bf16_f32 v231, v36, v37
	v_cvt_pk_bf16_f32 v232, v38, v39
	v_cvt_pk_bf16_f32 v233, v40, v41
	s_waitcnt lgkmcnt(2)
	s_nop 1
	v_mfma_f32_32x32x16_bf16 v[130:145], v[194:197], v[230:233], v[130:145]
	v_mfma_f32_32x32x16_bf16 v[234:249], v[218:221], v[230:233], v[234:249]
	ds_read2_b64 v[194:197], v251 offset0:88 offset1:90
	ds_read2_b64 v[218:221], v250 offset0:120 offset1:122
	s_nop 0
	v_cvt_pk_bf16_f32 v230, v42, v43
	v_cvt_pk_bf16_f32 v231, v44, v45
	v_cvt_pk_bf16_f32 v232, v46, v47
	v_cvt_pk_bf16_f32 v233, v48, v49
	s_waitcnt lgkmcnt(2)
	s_nop 1
	v_mfma_f32_32x32x16_bf16 v[130:145], v[222:225], v[230:233], v[130:145]
	v_mfma_f32_32x32x16_bf16 v[234:249], v[226:229], v[230:233], v[234:249]
	ds_read2_b64 v[222:225], v251 offset0:92 offset1:94
	ds_read2_b64 v[226:229], v250 offset0:124 offset1:126
	s_nop 0
	v_cvt_pk_bf16_f32 v230, v50, v51
	v_cvt_pk_bf16_f32 v231, v52, v53
	v_cvt_pk_bf16_f32 v232, v54, v55
	v_cvt_pk_bf16_f32 v233, v56, v57
	s_waitcnt lgkmcnt(2)
	s_nop 1
	v_mfma_f32_32x32x16_bf16 v[130:145], v[194:197], v[230:233], v[130:145]
	v_mfma_f32_32x32x16_bf16 v[234:249], v[218:221], v[230:233], v[234:249]
	ds_read2_b64 v[194:197], v251 offset0:96 offset1:98
	ds_read2_b64 v[218:221], v250 offset0:128 offset1:130
	s_nop 0
	v_cvt_pk_bf16_f32 v230, v58, v59
	v_cvt_pk_bf16_f32 v231, v60, v61
	v_cvt_pk_bf16_f32 v232, v62, v63
	v_cvt_pk_bf16_f32 v233, v64, v65
	s_waitcnt lgkmcnt(2)
	s_nop 1
	v_mfma_f32_32x32x16_bf16 v[130:145], v[222:225], v[230:233], v[130:145]
	v_mfma_f32_32x32x16_bf16 v[234:249], v[226:229], v[230:233], v[234:249]
	ds_read2_b64 v[222:225], v251 offset0:100 offset1:102
	ds_read2_b64 v[226:229], v250 offset0:132 offset1:134
	s_nop 0
	v_cvt_pk_bf16_f32 v230, v66, v67
	v_cvt_pk_bf16_f32 v231, v68, v69
	v_cvt_pk_bf16_f32 v232, v70, v71
	v_cvt_pk_bf16_f32 v233, v72, v73
	s_waitcnt lgkmcnt(2)
	s_nop 1
	v_mfma_f32_32x32x16_bf16 v[130:145], v[194:197], v[230:233], v[130:145]
	v_mfma_f32_32x32x16_bf16 v[234:249], v[218:221], v[230:233], v[234:249]
	ds_read2_b64 v[194:197], v251 offset0:104 offset1:106
	ds_read2_b64 v[218:221], v250 offset0:136 offset1:138
	s_nop 0
	v_cvt_pk_bf16_f32 v230, v74, v75
	v_cvt_pk_bf16_f32 v231, v76, v77
	v_cvt_pk_bf16_f32 v232, v78, v79
	v_cvt_pk_bf16_f32 v233, v80, v81
	s_waitcnt lgkmcnt(2)
	s_nop 1
	v_mfma_f32_32x32x16_bf16 v[130:145], v[222:225], v[230:233], v[130:145]
	v_mfma_f32_32x32x16_bf16 v[234:249], v[226:229], v[230:233], v[234:249]
	ds_read2_b64 v[222:225], v251 offset0:108 offset1:110
	ds_read2_b64 v[226:229], v250 offset0:140 offset1:142
	s_nop 0
	v_cvt_pk_bf16_f32 v230, v82, v83
	v_cvt_pk_bf16_f32 v231, v84, v85
	v_cvt_pk_bf16_f32 v232, v86, v87
	v_cvt_pk_bf16_f32 v233, v88, v89
	s_waitcnt lgkmcnt(2)
	s_nop 1
	v_mfma_f32_32x32x16_bf16 v[130:145], v[194:197], v[230:233], v[130:145]
	v_mfma_f32_32x32x16_bf16 v[234:249], v[218:221], v[230:233], v[234:249]
	ds_read2_b64 v[194:197], v251 offset0:112 offset1:114
	ds_read2_b64 v[218:221], v250 offset0:144 offset1:146
	s_nop 0
	v_cvt_pk_bf16_f32 v230, v90, v91
	v_cvt_pk_bf16_f32 v231, v92, v93
	v_cvt_pk_bf16_f32 v232, v94, v95
	v_cvt_pk_bf16_f32 v233, v96, v97
	s_waitcnt lgkmcnt(2)
	s_nop 1
	v_mfma_f32_32x32x16_bf16 v[130:145], v[222:225], v[230:233], v[130:145]
	v_mfma_f32_32x32x16_bf16 v[234:249], v[226:229], v[230:233], v[234:249]
	ds_read2_b64 v[222:225], v251 offset0:116 offset1:118
	ds_read2_b64 v[226:229], v250 offset0:148 offset1:150
	s_nop 0
	v_cvt_pk_bf16_f32 v230, v98, v99
	v_cvt_pk_bf16_f32 v231, v100, v101
	v_cvt_pk_bf16_f32 v232, v102, v103
	v_cvt_pk_bf16_f32 v233, v104, v105
	s_waitcnt lgkmcnt(2)
	s_nop 1
	v_mfma_f32_32x32x16_bf16 v[130:145], v[194:197], v[230:233], v[130:145]
	v_mfma_f32_32x32x16_bf16 v[234:249], v[218:221], v[230:233], v[234:249]
	ds_read2_b64 v[194:197], v251 offset0:120 offset1:122
	ds_read2_b64 v[218:221], v250 offset0:152 offset1:154
	s_nop 0
	v_cvt_pk_bf16_f32 v230, v106, v107
	v_cvt_pk_bf16_f32 v231, v108, v109
	v_cvt_pk_bf16_f32 v232, v110, v111
	v_cvt_pk_bf16_f32 v233, v112, v113
	s_waitcnt lgkmcnt(2)
	s_nop 1
	v_mfma_f32_32x32x16_bf16 v[130:145], v[222:225], v[230:233], v[130:145]
	v_mfma_f32_32x32x16_bf16 v[234:249], v[226:229], v[230:233], v[234:249]
	ds_read2_b64 v[222:225], v251 offset0:124 offset1:126
	ds_read2_b64 v[226:229], v250 offset0:156 offset1:158
	s_nop 0
	v_cvt_pk_bf16_f32 v230, v114, v115
	v_cvt_pk_bf16_f32 v231, v116, v117
	v_cvt_pk_bf16_f32 v232, v118, v119
	v_cvt_pk_bf16_f32 v233, v120, v121
	s_waitcnt lgkmcnt(2)
	s_nop 1
	v_mfma_f32_32x32x16_bf16 v[130:145], v[194:197], v[230:233], v[130:145]
	v_mfma_f32_32x32x16_bf16 v[234:249], v[218:221], v[230:233], v[234:249]
	s_nop 0
	v_cvt_pk_bf16_f32 v230, v122, v123
	v_cvt_pk_bf16_f32 v231, v124, v125
	v_cvt_pk_bf16_f32 v232, v126, v127
	v_cvt_pk_bf16_f32 v233, v128, v129
	s_waitcnt lgkmcnt(0)
	s_nop 1
	v_mfma_f32_32x32x16_bf16 v[130:145], v[222:225], v[230:233], v[130:145]
	v_mfma_f32_32x32x16_bf16 v[234:249], v[226:229], v[230:233], v[234:249]
	s_mov_b32 s100, 0xaaaaaaaa
	s_mov_b32 s101, 0xaaaaaaaa
	v_and_b32_e32 v220, 1, v189
	v_mul_u32_u24_e32 v220, 0xffe, v220
	v_mov_b32_e32 v221, 0
	v_lshl_add_u64 v[218:219], v[170:171], 0, v[172:173]
	v_lshl_add_u64 v[218:219], v[218:219], 0, v[220:221]
	s_mov_b32 s7, 0
	s_nop 7
	v_fmamk_f32 v222, v192, 0x42800000, v153
	v_fmamk_f32 v223, v192, 0x42820000, v153
	v_exp_f32_e32 v222, v222
	v_exp_f32_e32 v223, v223
	s_nop 0
	v_mul_f32_e32 v222, v222, v130
	v_mul_f32_e32 v223, v223, v131
	s_nop 1
	v_mov_b32_dpp v224, v222 quad_perm:[1,0,3,2] row_mask:0xf bank_mask:0xf
	v_mov_b32_dpp v225, v223 quad_perm:[1,0,3,2] row_mask:0xf bank_mask:0xf
	v_cndmask_b32_e64 v226, v222, v225, s[100:101]
	v_cndmask_b32_e64 v227, v224, v223, s[100:101]
	v_cvt_pk_bf16_f32 v226, v226, v227
	s_mov_b32 s6, 0x40000
	v_lshl_add_u64 v[228:229], v[218:219], 0, s[6:7]
	global_store_dword v[228:229], v226, off
	v_fmamk_f32 v222, v192, 0x42840000, v153
	v_fmamk_f32 v223, v192, 0x42860000, v153
	v_exp_f32_e32 v222, v222
	v_exp_f32_e32 v223, v223
	s_nop 0
	v_mul_f32_e32 v222, v222, v132
	v_mul_f32_e32 v223, v223, v133
	s_nop 1
	v_mov_b32_dpp v224, v222 quad_perm:[1,0,3,2] row_mask:0xf bank_mask:0xf
	v_mov_b32_dpp v225, v223 quad_perm:[1,0,3,2] row_mask:0xf bank_mask:0xf
	v_cndmask_b32_e64 v226, v222, v225, s[100:101]
	v_cndmask_b32_e64 v227, v224, v223, s[100:101]
	v_cvt_pk_bf16_f32 v226, v226, v227
	s_mov_b32 s6, 0x42000
	v_lshl_add_u64 v[228:229], v[218:219], 0, s[6:7]
	global_store_dword v[228:229], v226, off
	v_fmamk_f32 v222, v192, 0x42900000, v153
	v_fmamk_f32 v223, v192, 0x42920000, v153
	v_exp_f32_e32 v222, v222
	v_exp_f32_e32 v223, v223
	s_nop 0
	v_mul_f32_e32 v222, v222, v134
	v_mul_f32_e32 v223, v223, v135
	s_nop 1
	v_mov_b32_dpp v224, v222 quad_perm:[1,0,3,2] row_mask:0xf bank_mask:0xf
	v_mov_b32_dpp v225, v223 quad_perm:[1,0,3,2] row_mask:0xf bank_mask:0xf
	v_cndmask_b32_e64 v226, v222, v225, s[100:101]
	v_cndmask_b32_e64 v227, v224, v223, s[100:101]
	v_cvt_pk_bf16_f32 v226, v226, v227
	s_mov_b32 s6, 0x48000
	v_lshl_add_u64 v[228:229], v[218:219], 0, s[6:7]
	global_store_dword v[228:229], v226, off
	v_fmamk_f32 v222, v192, 0x42940000, v153
	v_fmamk_f32 v223, v192, 0x42960000, v153
	v_exp_f32_e32 v222, v222
	v_exp_f32_e32 v223, v223
	s_nop 0
	v_mul_f32_e32 v222, v222, v136
	v_mul_f32_e32 v223, v223, v137
	s_nop 1
	v_mov_b32_dpp v224, v222 quad_perm:[1,0,3,2] row_mask:0xf bank_mask:0xf
	v_mov_b32_dpp v225, v223 quad_perm:[1,0,3,2] row_mask:0xf bank_mask:0xf
	v_cndmask_b32_e64 v226, v222, v225, s[100:101]
	v_cndmask_b32_e64 v227, v224, v223, s[100:101]
	v_cvt_pk_bf16_f32 v226, v226, v227
	s_mov_b32 s6, 0x4a000
	v_lshl_add_u64 v[228:229], v[218:219], 0, s[6:7]
	global_store_dword v[228:229], v226, off
	v_fmamk_f32 v222, v192, 0x42a00000, v153
	v_fmamk_f32 v223, v192, 0x42a20000, v153
	v_exp_f32_e32 v222, v222
	v_exp_f32_e32 v223, v223
	s_nop 0
	v_mul_f32_e32 v222, v222, v138
	v_mul_f32_e32 v223, v223, v139
	s_nop 1
	v_mov_b32_dpp v224, v222 quad_perm:[1,0,3,2] row_mask:0xf bank_mask:0xf
	v_mov_b32_dpp v225, v223 quad_perm:[1,0,3,2] row_mask:0xf bank_mask:0xf
	v_cndmask_b32_e64 v226, v222, v225, s[100:101]
	v_cndmask_b32_e64 v227, v224, v223, s[100:101]
	v_cvt_pk_bf16_f32 v226, v226, v227
	s_mov_b32 s6, 0x50000
	v_lshl_add_u64 v[228:229], v[218:219], 0, s[6:7]
	global_store_dword v[228:229], v226, off
	v_fmamk_f32 v222, v192, 0x42a40000, v153
	v_fmamk_f32 v223, v192, 0x42a60000, v153
	v_exp_f32_e32 v222, v222
	v_exp_f32_e32 v223, v223
	s_nop 0
	v_mul_f32_e32 v222, v222, v140
	v_mul_f32_e32 v223, v223, v141
	s_nop 1
	v_mov_b32_dpp v224, v222 quad_perm:[1,0,3,2] row_mask:0xf bank_mask:0xf
	v_mov_b32_dpp v225, v223 quad_perm:[1,0,3,2] row_mask:0xf bank_mask:0xf
	v_cndmask_b32_e64 v226, v222, v225, s[100:101]
	v_cndmask_b32_e64 v227, v224, v223, s[100:101]
	v_cvt_pk_bf16_f32 v226, v226, v227
	s_mov_b32 s6, 0x52000
	v_lshl_add_u64 v[228:229], v[218:219], 0, s[6:7]
	global_store_dword v[228:229], v226, off
	v_fmamk_f32 v222, v192, 0x42b00000, v153
	v_fmamk_f32 v223, v192, 0x42b20000, v153
	v_exp_f32_e32 v222, v222
	v_exp_f32_e32 v223, v223
	s_nop 0
	v_mul_f32_e32 v222, v222, v142
	v_mul_f32_e32 v223, v223, v143
	s_nop 1
	v_mov_b32_dpp v224, v222 quad_perm:[1,0,3,2] row_mask:0xf bank_mask:0xf
	v_mov_b32_dpp v225, v223 quad_perm:[1,0,3,2] row_mask:0xf bank_mask:0xf
	v_cndmask_b32_e64 v226, v222, v225, s[100:101]
	v_cndmask_b32_e64 v227, v224, v223, s[100:101]
	v_cvt_pk_bf16_f32 v226, v226, v227
	s_mov_b32 s6, 0x58000
	v_lshl_add_u64 v[228:229], v[218:219], 0, s[6:7]
	global_store_dword v[228:229], v226, off
	v_fmamk_f32 v222, v192, 0x42b40000, v153
	v_fmamk_f32 v223, v192, 0x42b60000, v153
	v_exp_f32_e32 v222, v222
	v_exp_f32_e32 v223, v223
	s_nop 0
	v_mul_f32_e32 v222, v222, v144
	v_mul_f32_e32 v223, v223, v145
	s_nop 1
	v_mov_b32_dpp v224, v222 quad_perm:[1,0,3,2] row_mask:0xf bank_mask:0xf
	v_mov_b32_dpp v225, v223 quad_perm:[1,0,3,2] row_mask:0xf bank_mask:0xf
	v_cndmask_b32_e64 v226, v222, v225, s[100:101]
	v_cndmask_b32_e64 v227, v224, v223, s[100:101]
	v_cvt_pk_bf16_f32 v226, v226, v227
	s_mov_b32 s6, 0x5a000
	v_lshl_add_u64 v[228:229], v[218:219], 0, s[6:7]
	global_store_dword v[228:229], v226, off
	v_mov_b32_e32 v130, v234
	v_mov_b32_e32 v131, v235
	v_mov_b32_e32 v132, v236
	v_mov_b32_e32 v133, v237
	v_mov_b32_e32 v134, v238
	v_mov_b32_e32 v135, v239
	v_mov_b32_e32 v136, v240
	v_mov_b32_e32 v137, v241
	v_mov_b32_e32 v138, v242
	v_mov_b32_e32 v139, v243
	v_mov_b32_e32 v140, v244
	v_mov_b32_e32 v141, v245
	v_mov_b32_e32 v142, v246
	v_mov_b32_e32 v143, v247
	v_mov_b32_e32 v144, v248
	v_mov_b32_e32 v145, v249
	s_mov_b32 s100, 0xaaaaaaaa
	s_mov_b32 s101, 0xaaaaaaaa
	v_and_b32_e32 v220, 1, v189
	v_mul_u32_u24_e32 v220, 0xffe, v220
	v_mov_b32_e32 v221, 0
	v_lshl_add_u64 v[218:219], v[170:171], 0, v[172:173]
	v_lshl_add_u64 v[218:219], v[218:219], 0, v[220:221]
	s_mov_b32 s7, 0
	s_nop 7
	v_fmamk_f32 v222, v192, 0x42c00000, v153
	v_fmamk_f32 v223, v192, 0x42c20000, v153
	v_exp_f32_e32 v222, v222
	v_exp_f32_e32 v223, v223
	s_nop 0
	v_mul_f32_e32 v222, v222, v130
	v_mul_f32_e32 v223, v223, v131
	s_nop 1
	v_mov_b32_dpp v224, v222 quad_perm:[1,0,3,2] row_mask:0xf bank_mask:0xf
	v_mov_b32_dpp v225, v223 quad_perm:[1,0,3,2] row_mask:0xf bank_mask:0xf
	v_cndmask_b32_e64 v226, v222, v225, s[100:101]
	v_cndmask_b32_e64 v227, v224, v223, s[100:101]
	v_cvt_pk_bf16_f32 v226, v226, v227
	s_mov_b32 s6, 0x60000
	v_lshl_add_u64 v[228:229], v[218:219], 0, s[6:7]
	global_store_dword v[228:229], v226, off
	v_fmamk_f32 v222, v192, 0x42c40000, v153
	v_fmamk_f32 v223, v192, 0x42c60000, v153
	v_exp_f32_e32 v222, v222
	v_exp_f32_e32 v223, v223
	s_nop 0
	v_mul_f32_e32 v222, v222, v132
	v_mul_f32_e32 v223, v223, v133
	s_nop 1
	v_mov_b32_dpp v224, v222 quad_perm:[1,0,3,2] row_mask:0xf bank_mask:0xf
	v_mov_b32_dpp v225, v223 quad_perm:[1,0,3,2] row_mask:0xf bank_mask:0xf
	v_cndmask_b32_e64 v226, v222, v225, s[100:101]
	v_cndmask_b32_e64 v227, v224, v223, s[100:101]
	v_cvt_pk_bf16_f32 v226, v226, v227
	s_mov_b32 s6, 0x62000
	v_lshl_add_u64 v[228:229], v[218:219], 0, s[6:7]
	global_store_dword v[228:229], v226, off
	v_fmamk_f32 v222, v192, 0x42d00000, v153
	v_fmamk_f32 v223, v192, 0x42d20000, v153
	v_exp_f32_e32 v222, v222
	v_exp_f32_e32 v223, v223
	s_nop 0
	v_mul_f32_e32 v222, v222, v134
	v_mul_f32_e32 v223, v223, v135
	s_nop 1
	v_mov_b32_dpp v224, v222 quad_perm:[1,0,3,2] row_mask:0xf bank_mask:0xf
	v_mov_b32_dpp v225, v223 quad_perm:[1,0,3,2] row_mask:0xf bank_mask:0xf
	v_cndmask_b32_e64 v226, v222, v225, s[100:101]
	v_cndmask_b32_e64 v227, v224, v223, s[100:101]
	v_cvt_pk_bf16_f32 v226, v226, v227
	s_mov_b32 s6, 0x68000
	v_lshl_add_u64 v[228:229], v[218:219], 0, s[6:7]
	global_store_dword v[228:229], v226, off
	v_fmamk_f32 v222, v192, 0x42d40000, v153
	v_fmamk_f32 v223, v192, 0x42d60000, v153
	v_exp_f32_e32 v222, v222
	v_exp_f32_e32 v223, v223
	s_nop 0
	v_mul_f32_e32 v222, v222, v136
	v_mul_f32_e32 v223, v223, v137
	s_nop 1
	v_mov_b32_dpp v224, v222 quad_perm:[1,0,3,2] row_mask:0xf bank_mask:0xf
	v_mov_b32_dpp v225, v223 quad_perm:[1,0,3,2] row_mask:0xf bank_mask:0xf
	v_cndmask_b32_e64 v226, v222, v225, s[100:101]
	v_cndmask_b32_e64 v227, v224, v223, s[100:101]
	v_cvt_pk_bf16_f32 v226, v226, v227
	s_mov_b32 s6, 0x6a000
	v_lshl_add_u64 v[228:229], v[218:219], 0, s[6:7]
	global_store_dword v[228:229], v226, off
	v_fmamk_f32 v222, v192, 0x42e00000, v153
	v_fmamk_f32 v223, v192, 0x42e20000, v153
	v_exp_f32_e32 v222, v222
	v_exp_f32_e32 v223, v223
	s_nop 0
	v_mul_f32_e32 v222, v222, v138
	v_mul_f32_e32 v223, v223, v139
	s_nop 1
	v_mov_b32_dpp v224, v222 quad_perm:[1,0,3,2] row_mask:0xf bank_mask:0xf
	v_mov_b32_dpp v225, v223 quad_perm:[1,0,3,2] row_mask:0xf bank_mask:0xf
	v_cndmask_b32_e64 v226, v222, v225, s[100:101]
	v_cndmask_b32_e64 v227, v224, v223, s[100:101]
	v_cvt_pk_bf16_f32 v226, v226, v227
	s_mov_b32 s6, 0x70000
	v_lshl_add_u64 v[228:229], v[218:219], 0, s[6:7]
	global_store_dword v[228:229], v226, off
	v_fmamk_f32 v222, v192, 0x42e40000, v153
	v_fmamk_f32 v223, v192, 0x42e60000, v153
	v_exp_f32_e32 v222, v222
	v_exp_f32_e32 v223, v223
	s_nop 0
	v_mul_f32_e32 v222, v222, v140
	v_mul_f32_e32 v223, v223, v141
	s_nop 1
	v_mov_b32_dpp v224, v222 quad_perm:[1,0,3,2] row_mask:0xf bank_mask:0xf
	v_mov_b32_dpp v225, v223 quad_perm:[1,0,3,2] row_mask:0xf bank_mask:0xf
	v_cndmask_b32_e64 v226, v222, v225, s[100:101]
	v_cndmask_b32_e64 v227, v224, v223, s[100:101]
	v_cvt_pk_bf16_f32 v226, v226, v227
	s_mov_b32 s6, 0x72000
	v_lshl_add_u64 v[228:229], v[218:219], 0, s[6:7]
	global_store_dword v[228:229], v226, off
	v_fmamk_f32 v222, v192, 0x42f00000, v153
	v_fmamk_f32 v223, v192, 0x42f20000, v153
	v_exp_f32_e32 v222, v222
	v_exp_f32_e32 v223, v223
	s_nop 0
	v_mul_f32_e32 v222, v222, v142
	v_mul_f32_e32 v223, v223, v143
	s_nop 1
	v_mov_b32_dpp v224, v222 quad_perm:[1,0,3,2] row_mask:0xf bank_mask:0xf
	v_mov_b32_dpp v225, v223 quad_perm:[1,0,3,2] row_mask:0xf bank_mask:0xf
	v_cndmask_b32_e64 v226, v222, v225, s[100:101]
	v_cndmask_b32_e64 v227, v224, v223, s[100:101]
	v_cvt_pk_bf16_f32 v226, v226, v227
	s_mov_b32 s6, 0x78000
	v_lshl_add_u64 v[228:229], v[218:219], 0, s[6:7]
	global_store_dword v[228:229], v226, off
	v_fmamk_f32 v222, v192, 0x42f40000, v153
	v_fmamk_f32 v223, v192, 0x42f60000, v153
	v_exp_f32_e32 v222, v222
	v_exp_f32_e32 v223, v223
	s_nop 0
	v_mul_f32_e32 v222, v222, v144
	v_mul_f32_e32 v223, v223, v145
	s_nop 1
	v_mov_b32_dpp v224, v222 quad_perm:[1,0,3,2] row_mask:0xf bank_mask:0xf
	v_mov_b32_dpp v225, v223 quad_perm:[1,0,3,2] row_mask:0xf bank_mask:0xf
	v_cndmask_b32_e64 v226, v222, v225, s[100:101]
	v_cndmask_b32_e64 v227, v224, v223, s[100:101]
	v_cvt_pk_bf16_f32 v226, v226, v227
	s_mov_b32 s6, 0x7a000
	v_lshl_add_u64 v[228:229], v[218:219], 0, s[6:7]
	global_store_dword v[228:229], v226, off
	v_mov_b32_e32 v153, v189
	s_waitcnt vmcnt(63) expcnt(7) lgkmcnt(15)
	s_barrier
	v_lshl_add_u64 v[132:133], s[64:65], 0, v[164:165]
	v_lshlrev_b64 v[130:131], 1, v[168:169]
	v_lshlrev_b64 v[226:227], 14, v[166:167]
	v_lshl_add_u64 v[226:227], s[64:65], 0, v[226:227]
	v_lshl_add_u64 v[226:227], v[226:227], 0, v[130:131]
	v_mov_b32_e32 v228, v152
	v_mov_b32_e32 v229, v1
	v_lshl_add_u64 v[226:227], v[226:227], 0, v[228:229]
	s_mov_b64 s[6:7], 0xf640000
	v_lshl_add_u64 v[226:227], v[226:227], 0, s[6:7]
	global_load_dwordx4 v[234:237], v[226:227], off
	global_load_dwordx4 v[238:241], v[226:227], off offset:32
	global_load_dwordx4 v[242:245], v[226:227], off offset:64
	global_load_dwordx4 v[246:249], v[226:227], off offset:96
	v_lshl_add_u64 v[132:133], v[132:133], 0, v[130:131]
	v_lshlrev_b32_e32 v134, 4, v153
	v_and_b32_e32 v144, 0xf0, v134
	v_mov_b32_e32 v145, v1
	v_lshlrev_b32_e32 v134, 10, v153
	v_lshl_add_u64 v[132:133], v[132:133], 0, v[144:145]
	v_and_b32_e32 v134, 0x3c000, v134
	v_mov_b32_e32 v135, v1
	v_lshl_add_u64 v[172:173], v[132:133], 0, v[134:135]
	s_mov_b32 s6, 0xe640000
	v_add_co_u32_e64 v132, s[6:7], s6, v172
	v_bfe_u32 v145, v153, 4, 4
	s_nop 0
	v_addc_co_u32_e64 v133, s[6:7], 0, v173, s[6:7]
	s_mov_b32 s6, 0xe680000
	s_nop 0
	v_add_co_u32_e64 v136, s[6:7], s6, v172
	global_load_dwordx4 v[132:135], v[132:133], off
	s_nop 0
	v_addc_co_u32_e64 v137, s[6:7], 0, v173, s[6:7]
	s_mov_b32 s6, 0xe6c0000
	s_nop 0
	v_add_co_u32_e64 v140, s[6:7], s6, v172
	global_load_dwordx4 v[136:139], v[136:137], off
	s_nop 0
	v_addc_co_u32_e64 v141, s[6:7], 0, v173, s[6:7]
	s_mov_b32 s6, 0xe700000
	s_nop 0
	v_add_co_u32_e64 v168, s[6:7], s6, v172
	global_load_dwordx4 v[140:143], v[140:141], off
	s_nop 0
	v_addc_co_u32_e64 v169, s[6:7], 0, v173, s[6:7]
	s_mov_b32 s6, 0xe740000
	s_nop 0
	v_add_co_u32_e64 v192, s[6:7], s6, v172
	global_load_dwordx4 v[168:171], v[168:169], off
	s_nop 0
	v_addc_co_u32_e64 v193, s[6:7], 0, v173, s[6:7]
	s_mov_b32 s6, 0xe780000
	s_nop 0
	v_add_co_u32_e64 v196, s[6:7], s6, v172
	global_load_dwordx4 v[192:195], v[192:193], off
	s_nop 0
	v_addc_co_u32_e64 v197, s[6:7], 0, v173, s[6:7]
	s_mov_b32 s6, 0xe7c0000
	s_nop 0
	v_add_co_u32_e64 v208, s[6:7], s6, v172
	global_load_dwordx4 v[196:199], v[196:197], off
	s_nop 0
	v_addc_co_u32_e64 v209, s[6:7], 0, v173, s[6:7]
	s_mov_b32 s6, 0xe800000
	global_load_dwordx4 v[218:221], v[208:209], off
	v_add_co_u32_e64 v208, s[6:7], s6, v172
	v_mul_u32_u24_e32 v145, 0x108, v145
	s_nop 0
	v_addc_co_u32_e64 v209, s[6:7], 0, v173, s[6:7]
	global_load_dwordx4 v[222:225], v[208:209], off
	v_add3_u32 v153, v149, v144, v145
	s_waitcnt vmcnt(7)
	ds_write2_b64 v153, v[132:133], v[134:135] offset1:1
	v_add_u32_e32 v132, 0x1080, v153
	s_waitcnt vmcnt(6)
	ds_write2_b64 v132, v[136:137], v[138:139] offset1:1
	v_add_u32_e32 v132, 0x2100, v153
	s_waitcnt vmcnt(5)
	ds_write2_b64 v132, v[140:141], v[142:143] offset1:1
	v_add_u32_e32 v132, 0x3180, v153
	s_waitcnt vmcnt(4)
	ds_write2_b64 v132, v[168:169], v[170:171] offset1:1
	v_add_u32_e32 v132, 0x4200, v153
	s_waitcnt vmcnt(3)
	ds_write2_b64 v132, v[192:193], v[194:195] offset1:1
	v_add_u32_e32 v132, 0x5280, v153
	s_waitcnt vmcnt(2)
	ds_write2_b64 v132, v[196:197], v[198:199] offset1:1
	v_add_u32_e32 v132, 0x6300, v153
	s_waitcnt vmcnt(1)
	ds_write2_b64 v132, v[218:219], v[220:221] offset1:1
	v_add_u32_e32 v132, 0x7380, v153
	s_waitcnt vmcnt(0)
	ds_write2_b64 v132, v[222:223], v[224:225] offset1:1
	s_mov_b32 s6, 0xe840000
	v_add_co_u32_e64 v132, s[6:7], s6, v172
	s_nop 1
	v_addc_co_u32_e64 v133, s[6:7], 0, v173, s[6:7]
	s_mov_b32 s6, 0xe880000
	s_nop 0
	v_add_co_u32_e64 v136, s[6:7], s6, v172
	global_load_dwordx4 v[132:135], v[132:133], off
	s_nop 0
	v_addc_co_u32_e64 v137, s[6:7], 0, v173, s[6:7]
	s_mov_b32 s6, 0xe8c0000
	s_nop 0
	v_add_co_u32_e64 v140, s[6:7], s6, v172
	global_load_dwordx4 v[136:139], v[136:137], off
	s_nop 0
	v_addc_co_u32_e64 v141, s[6:7], 0, v173, s[6:7]
	s_mov_b32 s6, 0xe900000
	s_nop 0
	v_add_co_u32_e64 v144, s[6:7], s6, v172
	global_load_dwordx4 v[140:143], v[140:141], off
	s_nop 0
	v_addc_co_u32_e64 v145, s[6:7], 0, v173, s[6:7]
	s_mov_b32 s6, 0xe940000
	global_load_dwordx4 v[168:171], v[144:145], off
	v_add_co_u32_e64 v144, s[6:7], s6, v172
	s_nop 1
	v_addc_co_u32_e64 v145, s[6:7], 0, v173, s[6:7]
	s_mov_b32 s6, 0xe980000
	global_load_dwordx4 v[192:195], v[144:145], off
	v_add_co_u32_e64 v144, s[6:7], s6, v172
	s_nop 1
	v_addc_co_u32_e64 v145, s[6:7], 0, v173, s[6:7]
	s_mov_b32 s6, 0xe9c0000
	global_load_dwordx4 v[196:199], v[144:145], off
	v_add_co_u32_e64 v144, s[6:7], s6, v172
	s_nop 1
	v_addc_co_u32_e64 v145, s[6:7], 0, v173, s[6:7]
	s_mov_b32 s6, 0xea00000
	global_load_dwordx4 v[218:221], v[144:145], off
	v_add_co_u32_e64 v144, s[6:7], s6, v172
	s_nop 1
	v_addc_co_u32_e64 v145, s[6:7], 0, v173, s[6:7]
	global_load_dwordx4 v[222:225], v[144:145], off
	v_add_u32_e32 v144, 0x8400, v153
	s_waitcnt vmcnt(7)
	ds_write2_b64 v144, v[132:133], v[134:135] offset1:1
	v_add_u32_e32 v132, 0x9480, v153
	s_waitcnt vmcnt(6)
	ds_write2_b64 v132, v[136:137], v[138:139] offset1:1
	v_add_u32_e32 v132, 0xa500, v153
	s_waitcnt vmcnt(5)
	ds_write2_b64 v132, v[140:141], v[142:143] offset1:1
	v_add_u32_e32 v132, 0xb580, v153
	s_waitcnt vmcnt(4)
	ds_write2_b64 v132, v[168:169], v[170:171] offset1:1
	v_add_u32_e32 v132, 0xc600, v153
	s_waitcnt vmcnt(3)
	ds_write2_b64 v132, v[192:193], v[194:195] offset1:1
	v_add_u32_e32 v132, 0xd680, v153
	s_waitcnt vmcnt(2)
	ds_write2_b64 v132, v[196:197], v[198:199] offset1:1
	v_add_u32_e32 v132, 0xe700, v153
	s_waitcnt vmcnt(1)
	ds_write2_b64 v132, v[218:219], v[220:221] offset1:1
	v_add_u32_e32 v132, 0xf780, v153
	s_waitcnt vmcnt(0)
	ds_write2_b64 v132, v[222:223], v[224:225] offset1:1
	s_waitcnt lgkmcnt(0)
	s_barrier
	v_lshlrev_b64 v[132:133], 14, v[166:167]
	v_lshl_add_u64 v[132:133], s[64:65], 0, v[132:133]
	v_lshl_add_u64 v[130:131], v[132:133], 0, v[130:131]
	v_mov_b32_e32 v153, v1
	v_lshl_add_u64 v[134:135], v[130:131], 0, v[152:153]
	s_mov_b32 s6, 0xf640000
	v_add_co_u32_e64 v130, s[6:7], s6, v134
	v_mul_f32 v2, v2, v159
	v_mul_f32 v3, v3, v159
	v_mul_f32 v4, v4, v159
	v_mul_f32 v5, v5, v159
	s_nop 1
	v_addc_co_u32_e64 v131, s[6:7], 0, v135, s[6:7]
	v_mul_f32 v6, v6, v159
	v_mul_f32 v7, v7, v159
	v_mul_f32 v8, v8, v159
	v_mul_f32 v9, v9, v159
	v_mul_f32 v10, v10, v159
	v_mul_f32 v11, v11, v159
	v_mul_f32 v12, v12, v159
	v_mul_f32 v13, v13, v159
	v_mul_f32 v14, v14, v159
	v_mul_f32 v15, v15, v159
	v_mul_f32 v16, v16, v159
	v_mul_f32 v17, v17, v159
	v_mul_f32 v18, v18, v159
	v_mul_f32 v19, v19, v159
	v_mul_f32 v20, v20, v159
	v_mul_f32 v21, v21, v159
	v_mul_f32 v22, v22, v159
	v_mul_f32 v23, v23, v159
	v_mul_f32 v24, v24, v159
	v_mul_f32 v25, v25, v159
	v_mul_f32 v26, v26, v159
	v_mul_f32 v27, v27, v159
	v_mul_f32 v28, v28, v159
	v_mul_f32 v29, v29, v159
	v_mul_f32 v30, v30, v159
	v_mul_f32 v31, v31, v159
	v_mul_f32 v32, v32, v159
	v_mul_f32 v33, v33, v159
	v_mul_f32 v34, v34, v159
	v_mul_f32 v35, v35, v159
	v_mul_f32 v36, v36, v159
	v_mul_f32 v37, v37, v159
	v_mul_f32 v38, v38, v159
	v_mul_f32 v39, v39, v159
	v_mul_f32 v40, v40, v159
	v_mul_f32 v41, v41, v159
	v_mul_f32 v42, v42, v159
	v_mul_f32 v43, v43, v159
	v_mul_f32 v44, v44, v159
	v_mul_f32 v45, v45, v159
	v_mul_f32 v46, v46, v159
	v_mul_f32 v47, v47, v159
	v_mul_f32 v48, v48, v159
	v_mul_f32 v49, v49, v159
	v_mul_f32 v50, v50, v159
	v_mul_f32 v51, v51, v159
	v_mul_f32 v52, v52, v159
	v_mul_f32 v53, v53, v159
	v_mul_f32 v54, v54, v159
	v_mul_f32 v55, v55, v159
	v_mul_f32 v56, v56, v159
	v_mul_f32 v57, v57, v159
	v_mul_f32 v58, v58, v159
	v_mul_f32 v59, v59, v159
	v_mul_f32 v60, v60, v159
	v_mul_f32 v61, v61, v159
	v_mul_f32 v62, v62, v159
	v_mul_f32 v63, v63, v159
	v_mul_f32 v64, v64, v159
	v_mul_f32 v65, v65, v159
	v_mul_f32 v66, v66, v159
	v_mul_f32 v67, v67, v159
	v_mul_f32 v68, v68, v159
	v_mul_f32 v69, v69, v159
	v_mul_f32 v70, v70, v159
	v_mul_f32 v71, v71, v159
	v_mul_f32 v72, v72, v159
	v_mul_f32 v73, v73, v159
	v_mul_f32 v74, v74, v159
	v_mul_f32 v75, v75, v159
	v_mul_f32 v76, v76, v159
	v_mul_f32 v77, v77, v159
	v_mul_f32 v78, v78, v159
	v_mul_f32 v79, v79, v159
	v_mul_f32 v80, v80, v159
	v_mul_f32 v81, v81, v159
	v_mul_f32 v82, v82, v159
	v_mul_f32 v83, v83, v159
	v_mul_f32 v84, v84, v159
	v_mul_f32 v85, v85, v159
	v_mul_f32 v86, v86, v159
	v_mul_f32 v87, v87, v159
	v_mul_f32 v88, v88, v159
	v_mul_f32 v89, v89, v159
	v_mul_f32 v90, v90, v159
	v_mul_f32 v91, v91, v159
	v_mul_f32 v92, v92, v159
	v_mul_f32 v93, v93, v159
	v_mul_f32 v94, v94, v159
	v_mul_f32 v95, v95, v159
	v_mul_f32 v96, v96, v159
	v_mul_f32 v97, v97, v159
	v_mul_f32 v98, v98, v159
	v_mul_f32 v99, v99, v159
	v_mul_f32 v100, v100, v159
	v_mul_f32 v101, v101, v159
	v_mul_f32 v102, v102, v159
	v_mul_f32 v103, v103, v159
	v_mul_f32 v104, v104, v159
	v_mul_f32 v105, v105, v159
	v_mul_f32 v106, v106, v159
	v_mul_f32 v107, v107, v159
	v_mul_f32 v108, v108, v159
	v_mul_f32 v109, v109, v159
	v_mul_f32 v110, v110, v159
	v_mul_f32 v111, v111, v159
	v_mul_f32 v112, v112, v159
	v_mul_f32 v113, v113, v159
	v_mul_f32 v114, v114, v159
	v_mul_f32 v115, v115, v159
	v_mul_f32 v116, v116, v159
	v_mul_f32 v117, v117, v159
	v_mul_f32 v118, v118, v159
	v_mul_f32 v119, v119, v159
	v_mul_f32 v120, v120, v159
	v_mul_f32 v121, v121, v159
	v_mul_f32 v122, v122, v159
	v_mul_f32 v123, v123, v159
	v_mul_f32 v124, v124, v159
	v_mul_f32 v125, v125, v159
	v_mul_f32 v126, v126, v159
	v_mul_f32 v127, v127, v159
	v_mul_f32 v128, v128, v159
	v_mul_f32 v129, v129, v159
	s_mov_b64 s[6:7], 0xf640000
	v_lshl_add_u64 v[142:143], v[134:135], 0, s[6:7]
	v_mov_b32_e32 v130, v234
	v_mov_b32_e32 v131, v235
	v_mov_b32_e32 v132, v236
	v_mov_b32_e32 v133, v237
	v_mov_b32_e32 v134, v238
	v_mov_b32_e32 v135, v239
	v_mov_b32_e32 v136, v240
	v_mov_b32_e32 v137, v241
	v_mov_b32_e32 v138, v242
	v_mov_b32_e32 v139, v243
	v_mov_b32_e32 v140, v244
	v_mov_b32_e32 v141, v245
	v_mov_b32_e32 v166, v246
	v_mov_b32_e32 v167, v247
	v_mov_b32_e32 v168, v248
	v_mov_b32_e32 v169, v249
	global_load_dwordx4 v[234:237], v[142:143], off offset:128
	global_load_dwordx4 v[238:241], v[142:143], off offset:160
	global_load_dwordx4 v[242:245], v[142:143], off offset:192
	global_load_dwordx4 v[246:249], v[142:143], off offset:224
	v_fma_f32 v144, 0, v191, v190
	v_add_f32_e32 v145, v190, v191
	v_exp_f32_e32 v144, v144
	v_exp_f32_e32 v145, v145
	v_fmamk_f32 v153, v191, 0x42480000, v190
	s_waitcnt vmcnt(4)
	v_lshlrev_b32_e32 v170, 16, v130
	v_and_b32_e32 v171, 0xffff0000, v130
	v_fma_f32 v130, 2.0, v191, v190
	v_pk_mul_f32 v[144:145], v[144:145], v[170:171]
	v_exp_f32_e32 v170, v130
	v_fmamk_f32 v130, v191, 0x40400000, v190
	v_exp_f32_e32 v171, v130
	v_cvt_pk_bf16_f32 v130, v144, v145
	v_lshlrev_b32_e32 v144, 16, v131
	v_and_b32_e32 v145, 0xffff0000, v131
	v_fma_f32 v131, 4.0, v191, v190
	v_pk_mul_f32 v[144:145], v[170:171], v[144:145]
	v_exp_f32_e32 v170, v131
	v_fmamk_f32 v131, v191, 0x40a00000, v190
	v_exp_f32_e32 v171, v131
	v_cvt_pk_bf16_f32 v131, v144, v145
	v_lshlrev_b32_e32 v144, 16, v132
	v_and_b32_e32 v145, 0xffff0000, v132
	v_fmamk_f32 v132, v191, 0x40c00000, v190
	v_pk_mul_f32 v[144:145], v[170:171], v[144:145]
	v_exp_f32_e32 v170, v132
	v_fmamk_f32 v132, v191, 0x40e00000, v190
	v_exp_f32_e32 v171, v132
	v_cvt_pk_bf16_f32 v132, v144, v145
	v_lshlrev_b32_e32 v144, 16, v133
	v_and_b32_e32 v145, 0xffff0000, v133
	v_fmamk_f32 v133, v191, 0x41800000, v190
	v_pk_mul_f32 v[144:145], v[170:171], v[144:145]
	v_exp_f32_e32 v170, v133
	v_fmamk_f32 v133, v191, 0x41880000, v190
	v_exp_f32_e32 v171, v133
	v_cvt_pk_bf16_f32 v133, v144, v145
	s_waitcnt vmcnt(4)
	v_lshlrev_b32_e32 v144, 16, v134
	v_and_b32_e32 v145, 0xffff0000, v134
	v_fmamk_f32 v134, v191, 0x41900000, v190
	v_pk_mul_f32 v[144:145], v[170:171], v[144:145]
	v_exp_f32_e32 v170, v134
	v_fmamk_f32 v134, v191, 0x41980000, v190
	v_exp_f32_e32 v171, v134
	v_cvt_pk_bf16_f32 v134, v144, v145
	v_lshlrev_b32_e32 v144, 16, v135
	v_and_b32_e32 v145, 0xffff0000, v135
	v_fmamk_f32 v135, v191, 0x41a00000, v190
	v_pk_mul_f32 v[144:145], v[170:171], v[144:145]
	v_exp_f32_e32 v170, v135
	v_fmamk_f32 v135, v191, 0x41a80000, v190
	v_exp_f32_e32 v171, v135
	v_cvt_pk_bf16_f32 v135, v144, v145
	v_lshlrev_b32_e32 v144, 16, v136
	v_and_b32_e32 v145, 0xffff0000, v136
	v_fmamk_f32 v136, v191, 0x41b00000, v190
	v_pk_mul_f32 v[144:145], v[170:171], v[144:145]
	v_exp_f32_e32 v170, v136
	v_fmamk_f32 v136, v191, 0x41b80000, v190
	v_exp_f32_e32 v171, v136
	v_cvt_pk_bf16_f32 v136, v144, v145
	v_lshlrev_b32_e32 v144, 16, v137
	v_and_b32_e32 v145, 0xffff0000, v137
	v_fmamk_f32 v137, v191, 0x42000000, v190
	v_pk_mul_f32 v[144:145], v[170:171], v[144:145]
	v_exp_f32_e32 v170, v137
	v_fmamk_f32 v137, v191, 0x42040000, v190
	v_exp_f32_e32 v171, v137
	v_cvt_pk_bf16_f32 v137, v144, v145
	s_waitcnt vmcnt(4)
	v_lshlrev_b32_e32 v144, 16, v138
	v_and_b32_e32 v145, 0xffff0000, v138
	v_fmamk_f32 v138, v191, 0x42080000, v190
	v_pk_mul_f32 v[144:145], v[170:171], v[144:145]
	v_exp_f32_e32 v170, v138
	v_fmamk_f32 v138, v191, 0x420c0000, v190
	v_exp_f32_e32 v171, v138
	v_cvt_pk_bf16_f32 v138, v144, v145
	v_lshlrev_b32_e32 v144, 16, v139
	v_and_b32_e32 v145, 0xffff0000, v139
	v_fmamk_f32 v139, v191, 0x42100000, v190
	v_pk_mul_f32 v[144:145], v[170:171], v[144:145]
	v_exp_f32_e32 v170, v139
	v_fmamk_f32 v139, v191, 0x42140000, v190
	v_exp_f32_e32 v171, v139
	v_cvt_pk_bf16_f32 v139, v144, v145
	v_lshlrev_b32_e32 v144, 16, v140
	v_and_b32_e32 v145, 0xffff0000, v140
	v_fmamk_f32 v140, v191, 0x42180000, v190
	v_pk_mul_f32 v[144:145], v[170:171], v[144:145]
	v_exp_f32_e32 v170, v140
	v_fmamk_f32 v140, v191, 0x421c0000, v190
	v_exp_f32_e32 v171, v140
	v_cvt_pk_bf16_f32 v140, v144, v145
	v_lshlrev_b32_e32 v144, 16, v141
	v_and_b32_e32 v145, 0xffff0000, v141
	v_fmamk_f32 v141, v191, 0x42400000, v190
	v_pk_mul_f32 v[144:145], v[170:171], v[144:145]
	v_exp_f32_e32 v170, v141
	v_fmamk_f32 v141, v191, 0x42440000, v190
	v_exp_f32_e32 v171, v141
	v_cvt_pk_bf16_f32 v141, v144, v145
	s_waitcnt vmcnt(4)
	v_lshlrev_b32_e32 v144, 16, v166
	v_and_b32_e32 v145, 0xffff0000, v166
	v_pk_mul_f32 v[144:145], v[170:171], v[144:145]
	v_exp_f32_e32 v170, v153
	v_fmamk_f32 v153, v191, 0x424c0000, v190
	v_exp_f32_e32 v171, v153
	v_cvt_pk_bf16_f32 v166, v144, v145
	v_lshlrev_b32_e32 v144, 16, v167
	v_and_b32_e32 v145, 0xffff0000, v167
	v_fmamk_f32 v153, v191, 0x42500000, v190
	v_pk_mul_f32 v[144:145], v[170:171], v[144:145]
	v_exp_f32_e32 v170, v153
	v_fmamk_f32 v153, v191, 0x42540000, v190
	v_exp_f32_e32 v171, v153
	v_cvt_pk_bf16_f32 v167, v144, v145
	v_lshlrev_b32_e32 v144, 16, v168
	v_and_b32_e32 v145, 0xffff0000, v168
	v_fmamk_f32 v153, v191, 0x42580000, v190
	v_pk_mul_f32 v[144:145], v[170:171], v[144:145]
	v_exp_f32_e32 v170, v153
	v_fmamk_f32 v153, v191, 0x425c0000, v190
	v_exp_f32_e32 v171, v153
	v_cvt_pk_bf16_f32 v168, v144, v145
	v_lshlrev_b32_e32 v144, 16, v169
	v_and_b32_e32 v145, 0xffff0000, v169
	v_pk_mul_f32 v[144:145], v[170:171], v[144:145]
	s_nop 0
	v_cvt_pk_bf16_f32 v169, v144, v145
	ds_read2_b64 v[170:173], v179 offset1:1
	ds_read2_b64 v[192:195], v179 offset0:4 offset1:5
	ds_read2_b64 v[196:199], v179 offset0:8 offset1:9
	ds_read2_b64 v[218:221], v179 offset0:12 offset1:13
	s_waitcnt lgkmcnt(3)
	v_mfma_f32_32x32x16_bf16 v[2:17], v[170:173], v[130:133], v[2:17]
	v_add_u32_e32 v144, 0x2100, v179
	ds_read2_b64 v[170:173], v144 offset1:1
	s_waitcnt lgkmcnt(3)
	v_mfma_f32_32x32x16_bf16 v[2:17], v[192:195], v[134:137], v[2:17]
	v_add_u32_e32 v144, 0x2120, v179
	ds_read2_b64 v[192:195], v144 offset1:1
	s_waitcnt lgkmcnt(3)
	v_mfma_f32_32x32x16_bf16 v[2:17], v[196:199], v[138:141], v[2:17]
	v_add_u32_e32 v144, 0x2140, v179
	ds_read2_b64 v[196:199], v144 offset1:1
	s_waitcnt lgkmcnt(3)
	v_mfma_f32_32x32x16_bf16 v[2:17], v[218:221], v[166:169], v[2:17]
	v_add_u32_e32 v144, 0x2160, v179
	ds_read2_b64 v[218:221], v144 offset1:1
	s_waitcnt lgkmcnt(3)
	v_mfma_f32_32x32x16_bf16 v[18:33], v[170:173], v[130:133], v[18:33]
	v_add_u32_e32 v144, 0x4200, v179
	ds_read2_b64 v[170:173], v144 offset1:1
	s_waitcnt lgkmcnt(3)
	v_mfma_f32_32x32x16_bf16 v[18:33], v[192:195], v[134:137], v[18:33]
	v_add_u32_e32 v144, 0x4220, v179
	ds_read2_b64 v[192:195], v144 offset1:1
	s_waitcnt lgkmcnt(3)
	v_mfma_f32_32x32x16_bf16 v[18:33], v[196:199], v[138:141], v[18:33]
	v_add_u32_e32 v144, 0x4240, v179
	ds_read2_b64 v[196:199], v144 offset1:1
	s_waitcnt lgkmcnt(3)
	v_mfma_f32_32x32x16_bf16 v[18:33], v[218:221], v[166:169], v[18:33]
	v_add_u32_e32 v144, 0x4260, v179
	ds_read2_b64 v[218:221], v144 offset1:1
	s_waitcnt lgkmcnt(3)
	v_mfma_f32_32x32x16_bf16 v[34:49], v[170:173], v[130:133], v[34:49]
	v_add_u32_e32 v144, 0x6300, v179
	ds_read2_b64 v[170:173], v144 offset1:1
	s_waitcnt lgkmcnt(3)
	v_mfma_f32_32x32x16_bf16 v[34:49], v[192:195], v[134:137], v[34:49]
	v_add_u32_e32 v144, 0x6320, v179
	ds_read2_b64 v[192:195], v144 offset1:1
	s_waitcnt lgkmcnt(3)
	v_mfma_f32_32x32x16_bf16 v[34:49], v[196:199], v[138:141], v[34:49]
	v_add_u32_e32 v144, 0x6340, v179
	ds_read2_b64 v[196:199], v144 offset1:1
	s_waitcnt lgkmcnt(3)
	v_mfma_f32_32x32x16_bf16 v[34:49], v[218:221], v[166:169], v[34:49]
	v_add_u32_e32 v144, 0x6360, v179
	ds_read2_b64 v[218:221], v144 offset1:1
	s_waitcnt lgkmcnt(3)
	v_mfma_f32_32x32x16_bf16 v[50:65], v[170:173], v[130:133], v[50:65]
	v_add_u32_e32 v144, 0x8400, v179
	ds_read2_b64 v[170:173], v144 offset1:1
	s_waitcnt lgkmcnt(3)
	v_mfma_f32_32x32x16_bf16 v[50:65], v[192:195], v[134:137], v[50:65]
	v_add_u32_e32 v144, 0x8420, v179
	ds_read2_b64 v[192:195], v144 offset1:1
	s_waitcnt lgkmcnt(3)
	v_mfma_f32_32x32x16_bf16 v[50:65], v[196:199], v[138:141], v[50:65]
	v_add_u32_e32 v144, 0x8440, v179
	ds_read2_b64 v[196:199], v144 offset1:1
	s_waitcnt lgkmcnt(3)
	v_mfma_f32_32x32x16_bf16 v[50:65], v[218:221], v[166:169], v[50:65]
	v_add_u32_e32 v144, 0x8460, v179
	ds_read2_b64 v[218:221], v144 offset1:1
	s_waitcnt lgkmcnt(3)
	v_mfma_f32_32x32x16_bf16 v[66:81], v[170:173], v[130:133], v[66:81]
	v_add_u32_e32 v144, 0xa500, v179
	ds_read2_b64 v[170:173], v144 offset1:1
	s_waitcnt lgkmcnt(3)
	v_mfma_f32_32x32x16_bf16 v[66:81], v[192:195], v[134:137], v[66:81]
	v_add_u32_e32 v144, 0xa520, v179
	ds_read2_b64 v[192:195], v144 offset1:1
	s_waitcnt lgkmcnt(3)
	v_mfma_f32_32x32x16_bf16 v[66:81], v[196:199], v[138:141], v[66:81]
	v_add_u32_e32 v144, 0xa540, v179
	ds_read2_b64 v[196:199], v144 offset1:1
	s_waitcnt lgkmcnt(3)
	v_mfma_f32_32x32x16_bf16 v[66:81], v[218:221], v[166:169], v[66:81]
	v_add_u32_e32 v144, 0xa560, v179
	ds_read2_b64 v[218:221], v144 offset1:1
	s_waitcnt lgkmcnt(3)
	v_mfma_f32_32x32x16_bf16 v[82:97], v[170:173], v[130:133], v[82:97]
	v_add_u32_e32 v144, 0xc600, v179
	ds_read2_b64 v[170:173], v144 offset1:1
	s_waitcnt lgkmcnt(3)
	v_mfma_f32_32x32x16_bf16 v[82:97], v[192:195], v[134:137], v[82:97]
	v_add_u32_e32 v144, 0xc620, v179
	ds_read2_b64 v[192:195], v144 offset1:1
	s_waitcnt lgkmcnt(3)
	v_mfma_f32_32x32x16_bf16 v[82:97], v[196:199], v[138:141], v[82:97]
	v_add_u32_e32 v144, 0xc640, v179
	ds_read2_b64 v[196:199], v144 offset1:1
	s_waitcnt lgkmcnt(3)
	v_mfma_f32_32x32x16_bf16 v[82:97], v[218:221], v[166:169], v[82:97]
	v_add_u32_e32 v144, 0xc660, v179
	ds_read2_b64 v[218:221], v144 offset1:1
	s_waitcnt lgkmcnt(3)
	v_mfma_f32_32x32x16_bf16 v[98:113], v[170:173], v[130:133], v[98:113]
	v_add_u32_e32 v144, 0xe700, v179
	ds_read2_b64 v[170:173], v144 offset1:1
	s_waitcnt lgkmcnt(3)
	v_mfma_f32_32x32x16_bf16 v[98:113], v[192:195], v[134:137], v[98:113]
	v_add_u32_e32 v144, 0xe720, v179
	ds_read2_b64 v[192:195], v144 offset1:1
	s_waitcnt lgkmcnt(3)
	v_mfma_f32_32x32x16_bf16 v[98:113], v[196:199], v[138:141], v[98:113]
	v_add_u32_e32 v144, 0xe740, v179
	ds_read2_b64 v[196:199], v144 offset1:1
	s_waitcnt lgkmcnt(3)
	v_mfma_f32_32x32x16_bf16 v[98:113], v[218:221], v[166:169], v[98:113]
	v_add_u32_e32 v144, 0xe760, v179
	ds_read2_b64 v[218:221], v144 offset1:1
	s_waitcnt lgkmcnt(3)
	v_mfma_f32_32x32x16_bf16 v[114:129], v[170:173], v[130:133], v[114:129]
	s_waitcnt lgkmcnt(2)
	v_mfma_f32_32x32x16_bf16 v[114:129], v[192:195], v[134:137], v[114:129]
	s_waitcnt lgkmcnt(1)
	v_mfma_f32_32x32x16_bf16 v[114:129], v[196:199], v[138:141], v[114:129]
	s_waitcnt lgkmcnt(0)
	v_mfma_f32_32x32x16_bf16 v[114:129], v[218:221], v[166:169], v[114:129]
	v_fmamk_f32 v134, v191, 0x42800000, v190
	v_fmamk_f32 v135, v191, 0x42820000, v190
	v_exp_f32_e32 v134, v134
	v_exp_f32_e32 v135, v135
	v_fmamk_f32 v138, v191, 0x42a00000, v190
	v_fmamk_f32 v139, v191, 0x42a20000, v190
	v_exp_f32_e32 v138, v138
	v_exp_f32_e32 v139, v139
	v_fmamk_f32 v144, v191, 0x42c00000, v190
	v_fmamk_f32 v145, v191, 0x42c20000, v190
	v_exp_f32_e32 v144, v144
	v_exp_f32_e32 v145, v145
	v_fmamk_f32 v153, v191, 0x42e00000, v190
	s_waitcnt vmcnt(0)
	v_mov_b32_e32 v130, v234
	v_mov_b32_e32 v131, v235
	v_mov_b32_e32 v132, v236
	v_mov_b32_e32 v133, v237
	v_lshlrev_b32_e32 v136, 16, v130
	v_and_b32_e32 v137, 0xffff0000, v130
	v_pk_mul_f32 v[134:135], v[134:135], v[136:137]
	v_lshlrev_b32_e32 v136, 16, v131
	v_cvt_pk_bf16_f32 v130, v134, v135
	v_fmamk_f32 v134, v191, 0x42840000, v190
	v_fmamk_f32 v135, v191, 0x42860000, v190
	v_exp_f32_e32 v134, v134
	v_exp_f32_e32 v135, v135
	v_and_b32_e32 v137, 0xffff0000, v131
	v_pk_mul_f32 v[134:135], v[134:135], v[136:137]
	s_nop 0
	v_cvt_pk_bf16_f32 v131, v134, v135
	v_fmamk_f32 v134, v191, 0x42880000, v190
	v_fmamk_f32 v135, v191, 0x428a0000, v190
	v_exp_f32_e32 v134, v134
	v_exp_f32_e32 v135, v135
	v_lshlrev_b32_e32 v136, 16, v132
	v_and_b32_e32 v137, 0xffff0000, v132
	v_pk_mul_f32 v[134:135], v[134:135], v[136:137]
	s_nop 0
	v_cvt_pk_bf16_f32 v132, v134, v135
	v_fmamk_f32 v134, v191, 0x428c0000, v190
	v_fmamk_f32 v135, v191, 0x428e0000, v190
	v_exp_f32_e32 v134, v134
	v_exp_f32_e32 v135, v135
	v_lshlrev_b32_e32 v136, 16, v133
	v_and_b32_e32 v137, 0xffff0000, v133
	v_pk_mul_f32 v[134:135], v[134:135], v[136:137]
	s_nop 0
	v_cvt_pk_bf16_f32 v133, v134, v135
	s_waitcnt vmcnt(0)
	v_mov_b32_e32 v134, v238
	v_mov_b32_e32 v135, v239
	v_mov_b32_e32 v136, v240
	v_mov_b32_e32 v137, v241
	v_lshlrev_b32_e32 v140, 16, v134
	v_and_b32_e32 v141, 0xffff0000, v134
	v_pk_mul_f32 v[138:139], v[138:139], v[140:141]
	v_lshlrev_b32_e32 v140, 16, v135
	v_cvt_pk_bf16_f32 v134, v138, v139
	v_fmamk_f32 v138, v191, 0x42a40000, v190
	v_fmamk_f32 v139, v191, 0x42a60000, v190
	v_exp_f32_e32 v138, v138
	v_exp_f32_e32 v139, v139
	v_and_b32_e32 v141, 0xffff0000, v135
	v_pk_mul_f32 v[138:139], v[138:139], v[140:141]
	s_nop 0
	v_cvt_pk_bf16_f32 v135, v138, v139
	v_fmamk_f32 v138, v191, 0x42a80000, v190
	v_fmamk_f32 v139, v191, 0x42aa0000, v190
	v_exp_f32_e32 v138, v138
	v_exp_f32_e32 v139, v139
	v_lshlrev_b32_e32 v140, 16, v136
	v_and_b32_e32 v141, 0xffff0000, v136
	v_pk_mul_f32 v[138:139], v[138:139], v[140:141]
	s_nop 0
	v_cvt_pk_bf16_f32 v136, v138, v139
	v_fmamk_f32 v138, v191, 0x42ac0000, v190
	v_fmamk_f32 v139, v191, 0x42ae0000, v190
	v_exp_f32_e32 v138, v138
	v_exp_f32_e32 v139, v139
	v_lshlrev_b32_e32 v140, 16, v137
	v_and_b32_e32 v141, 0xffff0000, v137
	v_pk_mul_f32 v[138:139], v[138:139], v[140:141]
	s_nop 0
	v_cvt_pk_bf16_f32 v137, v138, v139
	s_waitcnt vmcnt(0)
	v_mov_b32_e32 v138, v242
	v_mov_b32_e32 v139, v243
	v_mov_b32_e32 v140, v244
	v_mov_b32_e32 v141, v245
	v_lshlrev_b32_e32 v166, 16, v138
	v_and_b32_e32 v167, 0xffff0000, v138
	v_pk_mul_f32 v[144:145], v[144:145], v[166:167]
	v_lshlrev_b32_e32 v166, 16, v139
	v_cvt_pk_bf16_f32 v138, v144, v145
	v_fmamk_f32 v144, v191, 0x42c40000, v190
	v_fmamk_f32 v145, v191, 0x42c60000, v190
	v_exp_f32_e32 v144, v144
	v_exp_f32_e32 v145, v145
	v_and_b32_e32 v167, 0xffff0000, v139
	v_pk_mul_f32 v[144:145], v[144:145], v[166:167]
	s_nop 0
	v_cvt_pk_bf16_f32 v139, v144, v145
	v_fmamk_f32 v144, v191, 0x42c80000, v190
	v_fmamk_f32 v145, v191, 0x42ca0000, v190
	v_exp_f32_e32 v144, v144
	v_exp_f32_e32 v145, v145
	v_lshlrev_b32_e32 v166, 16, v140
	v_and_b32_e32 v167, 0xffff0000, v140
	v_pk_mul_f32 v[144:145], v[144:145], v[166:167]
	s_nop 0
	v_cvt_pk_bf16_f32 v140, v144, v145
	v_fmamk_f32 v144, v191, 0x42cc0000, v190
	v_fmamk_f32 v145, v191, 0x42ce0000, v190
	v_exp_f32_e32 v144, v144
	v_exp_f32_e32 v145, v145
	v_lshlrev_b32_e32 v166, 16, v141
	v_and_b32_e32 v167, 0xffff0000, v141
	v_pk_mul_f32 v[144:145], v[144:145], v[166:167]
	s_nop 0
	v_cvt_pk_bf16_f32 v141, v144, v145
	v_exp_f32_e32 v166, v153
	v_fmamk_f32 v153, v191, 0x42e20000, v190
	v_exp_f32_e32 v167, v153
	v_fmamk_f32 v153, v191, 0x42e40000, v190
	s_waitcnt vmcnt(0)
	v_mov_b32_e32 v142, v246
	v_mov_b32_e32 v143, v247
	v_mov_b32_e32 v144, v248
	v_mov_b32_e32 v145, v249
	v_lshlrev_b32_e32 v168, 16, v142
	v_and_b32_e32 v169, 0xffff0000, v142
	v_pk_mul_f32 v[166:167], v[166:167], v[168:169]
	v_lshlrev_b32_e32 v168, 16, v143
	v_cvt_pk_bf16_f32 v142, v166, v167
	v_exp_f32_e32 v166, v153
	v_fmamk_f32 v153, v191, 0x42e60000, v190
	v_exp_f32_e32 v167, v153
	v_and_b32_e32 v169, 0xffff0000, v143
	v_fmamk_f32 v153, v191, 0x42e80000, v190
	v_pk_mul_f32 v[166:167], v[166:167], v[168:169]
	s_nop 0
	v_cvt_pk_bf16_f32 v143, v166, v167
	v_exp_f32_e32 v166, v153
	v_fmamk_f32 v153, v191, 0x42ea0000, v190
	v_exp_f32_e32 v167, v153
	v_lshlrev_b32_e32 v168, 16, v144
	v_and_b32_e32 v169, 0xffff0000, v144
	v_fmamk_f32 v153, v191, 0x42ec0000, v190
	v_pk_mul_f32 v[166:167], v[166:167], v[168:169]
	v_fmac_f32_e32 v190, 0x42ee0000, v191
	v_cvt_pk_bf16_f32 v144, v166, v167
	v_exp_f32_e32 v166, v153
	v_exp_f32_e32 v167, v190
	v_lshlrev_b32_e32 v168, 16, v145
	v_and_b32_e32 v169, 0xffff0000, v145
	v_pk_mul_f32 v[166:167], v[166:167], v[168:169]
	s_nop 0
	v_cvt_pk_bf16_f32 v145, v166, v167
	ds_read2_b64 v[166:169], v179 offset0:16 offset1:17
	ds_read2_b64 v[170:173], v179 offset0:20 offset1:21
	ds_read2_b64 v[190:193], v179 offset0:24 offset1:25
	ds_read2_b64 v[194:197], v179 offset0:28 offset1:29
	s_waitcnt lgkmcnt(3)
	v_mfma_f32_32x32x16_bf16 v[2:17], v[166:169], v[130:133], v[2:17]
	v_add_u32_e32 v153, 0x2180, v179
	ds_read2_b64 v[166:169], v153 offset1:1
	s_waitcnt lgkmcnt(3)
	v_mfma_f32_32x32x16_bf16 v[2:17], v[170:173], v[134:137], v[2:17]
	v_add_u32_e32 v153, 0x21a0, v179
	ds_read2_b64 v[170:173], v153 offset1:1
	s_waitcnt lgkmcnt(3)
	v_mfma_f32_32x32x16_bf16 v[2:17], v[190:193], v[138:141], v[2:17]
	v_add_u32_e32 v153, 0x21c0, v179
	ds_read2_b64 v[190:193], v153 offset1:1
	s_waitcnt lgkmcnt(3)
	v_mfma_f32_32x32x16_bf16 v[2:17], v[194:197], v[142:145], v[2:17]
	v_add_u32_e32 v153, 0x21e0, v179
	ds_read2_b64 v[194:197], v153 offset1:1
	s_waitcnt lgkmcnt(3)
	v_mfma_f32_32x32x16_bf16 v[18:33], v[166:169], v[130:133], v[18:33]
	v_add_u32_e32 v153, 0x4280, v179
	ds_read2_b64 v[166:169], v153 offset1:1
	s_waitcnt lgkmcnt(3)
	v_mfma_f32_32x32x16_bf16 v[18:33], v[170:173], v[134:137], v[18:33]
	v_add_u32_e32 v153, 0x42a0, v179
	ds_read2_b64 v[170:173], v153 offset1:1
	s_waitcnt lgkmcnt(3)
	v_mfma_f32_32x32x16_bf16 v[18:33], v[190:193], v[138:141], v[18:33]
	v_add_u32_e32 v153, 0x42c0, v179
	ds_read2_b64 v[190:193], v153 offset1:1
	s_waitcnt lgkmcnt(3)
	v_mfma_f32_32x32x16_bf16 v[18:33], v[194:197], v[142:145], v[18:33]
	v_add_u32_e32 v153, 0x42e0, v179
	ds_read2_b64 v[194:197], v153 offset1:1
	s_waitcnt lgkmcnt(3)
	v_mfma_f32_32x32x16_bf16 v[34:49], v[166:169], v[130:133], v[34:49]
	v_add_u32_e32 v153, 0x6380, v179
	ds_read2_b64 v[166:169], v153 offset1:1
	s_waitcnt lgkmcnt(3)
	v_mfma_f32_32x32x16_bf16 v[34:49], v[170:173], v[134:137], v[34:49]
	v_add_u32_e32 v153, 0x63a0, v179
	ds_read2_b64 v[170:173], v153 offset1:1
	s_waitcnt lgkmcnt(3)
	v_mfma_f32_32x32x16_bf16 v[34:49], v[190:193], v[138:141], v[34:49]
	v_add_u32_e32 v153, 0x63c0, v179
	ds_read2_b64 v[190:193], v153 offset1:1
	s_waitcnt lgkmcnt(3)
	v_mfma_f32_32x32x16_bf16 v[34:49], v[194:197], v[142:145], v[34:49]
	v_add_u32_e32 v153, 0x63e0, v179
	ds_read2_b64 v[194:197], v153 offset1:1
	s_waitcnt lgkmcnt(3)
	v_mfma_f32_32x32x16_bf16 v[50:65], v[166:169], v[130:133], v[50:65]
	v_add_u32_e32 v153, 0x8480, v179
	ds_read2_b64 v[166:169], v153 offset1:1
	s_waitcnt lgkmcnt(3)
	v_mfma_f32_32x32x16_bf16 v[50:65], v[170:173], v[134:137], v[50:65]
	v_add_u32_e32 v153, 0x84a0, v179
	ds_read2_b64 v[170:173], v153 offset1:1
	s_waitcnt lgkmcnt(3)
	v_mfma_f32_32x32x16_bf16 v[50:65], v[190:193], v[138:141], v[50:65]
	v_add_u32_e32 v153, 0x84c0, v179
	ds_read2_b64 v[190:193], v153 offset1:1
	s_waitcnt lgkmcnt(3)
	v_mfma_f32_32x32x16_bf16 v[50:65], v[194:197], v[142:145], v[50:65]
	v_add_u32_e32 v153, 0x84e0, v179
	ds_read2_b64 v[194:197], v153 offset1:1
	s_waitcnt lgkmcnt(3)
	v_mfma_f32_32x32x16_bf16 v[66:81], v[166:169], v[130:133], v[66:81]
	v_add_u32_e32 v153, 0xa580, v179
	ds_read2_b64 v[166:169], v153 offset1:1
	s_waitcnt lgkmcnt(3)
	v_mfma_f32_32x32x16_bf16 v[66:81], v[170:173], v[134:137], v[66:81]
	v_add_u32_e32 v153, 0xa5a0, v179
	ds_read2_b64 v[170:173], v153 offset1:1
	s_waitcnt lgkmcnt(3)
	v_mfma_f32_32x32x16_bf16 v[66:81], v[190:193], v[138:141], v[66:81]
	v_add_u32_e32 v153, 0xa5c0, v179
	ds_read2_b64 v[190:193], v153 offset1:1
	s_waitcnt lgkmcnt(3)
	v_mfma_f32_32x32x16_bf16 v[66:81], v[194:197], v[142:145], v[66:81]
	v_add_u32_e32 v153, 0xa5e0, v179
	ds_read2_b64 v[194:197], v153 offset1:1
	s_waitcnt lgkmcnt(3)
	v_mfma_f32_32x32x16_bf16 v[82:97], v[166:169], v[130:133], v[82:97]
	v_add_u32_e32 v153, 0xc680, v179
	ds_read2_b64 v[166:169], v153 offset1:1
	s_waitcnt lgkmcnt(3)
	v_mfma_f32_32x32x16_bf16 v[82:97], v[170:173], v[134:137], v[82:97]
	v_add_u32_e32 v153, 0xc6a0, v179
	ds_read2_b64 v[170:173], v153 offset1:1
	s_waitcnt lgkmcnt(3)
	v_mfma_f32_32x32x16_bf16 v[82:97], v[190:193], v[138:141], v[82:97]
	v_add_u32_e32 v153, 0xc6c0, v179
	ds_read2_b64 v[190:193], v153 offset1:1
	s_waitcnt lgkmcnt(3)
	v_mfma_f32_32x32x16_bf16 v[82:97], v[194:197], v[142:145], v[82:97]
	v_add_u32_e32 v153, 0xc6e0, v179
	ds_read2_b64 v[194:197], v153 offset1:1
	s_waitcnt lgkmcnt(3)
	v_mfma_f32_32x32x16_bf16 v[98:113], v[166:169], v[130:133], v[98:113]
	v_add_u32_e32 v153, 0xe780, v179
	ds_read2_b64 v[166:169], v153 offset1:1
	s_waitcnt lgkmcnt(3)
	v_mfma_f32_32x32x16_bf16 v[98:113], v[170:173], v[134:137], v[98:113]
	v_add_u32_e32 v153, 0xe7a0, v179
	ds_read2_b64 v[170:173], v153 offset1:1
	s_waitcnt lgkmcnt(3)
	v_mfma_f32_32x32x16_bf16 v[98:113], v[190:193], v[138:141], v[98:113]
	v_add_u32_e32 v153, 0xe7c0, v179
	ds_read2_b64 v[190:193], v153 offset1:1
	s_waitcnt lgkmcnt(3)
	v_mfma_f32_32x32x16_bf16 v[98:113], v[194:197], v[142:145], v[98:113]
	v_add_u32_e32 v153, 0xe7e0, v179
	ds_read2_b64 v[194:197], v153 offset1:1
	s_waitcnt lgkmcnt(3)
	v_mfma_f32_32x32x16_bf16 v[114:129], v[166:169], v[130:133], v[114:129]
	s_waitcnt lgkmcnt(2)
	v_mfma_f32_32x32x16_bf16 v[114:129], v[170:173], v[134:137], v[114:129]
	s_waitcnt lgkmcnt(1)
	v_mfma_f32_32x32x16_bf16 v[114:129], v[190:193], v[138:141], v[114:129]
	s_waitcnt lgkmcnt(0)
	v_mfma_f32_32x32x16_bf16 v[114:129], v[194:197], v[142:145], v[114:129]
	s_add_i32 s66, s66, 1
	s_add_i32 s67, s67, -1
	s_cmp_eq_u32 s67, -1
	s_cbranch_scc0 .LBB0_327
	s_and_b64 vcc, exec, s[4:5]
	s_mov_b64 s[4:5], -1
	s_cbranch_vccnz .LBB0_330
	s_mov_b64 s[4:5], 0
